# code placement: every 32-MFMA block of the six live GEMM K-loops starts 8-byte aligned (one s_nop 0 pad ahead of a load segment's closing waits where needed); stacked on stack24
# speedup vs baseline: 1.0015x; 1.0015x over previous
; #define PG8_STAGE(bufoff, gbase, voff) do { _Pragma("unroll") for (int _i = 0; _i < 2; ++_i) \
;         __builtin_amdgcn_global_load_lds((const unsigned*)((const char*)(gbase) + (voff)[_i]), (PG8_LAS unsigned*)(lds + (bufoff) + ldsw + _i * 8192), 16, 0, 0); } while (0)
; #define PG8_LDA(dst, b, h) do { _Pragma("unroll") for (int m = 0; m < 4; ++m) _Pragma("unroll") for (int k = 0; k < 2; ++k) dst[m][k] = *(const PG8_LAS bf16x8*)(lds + PG8_SA(b, h) + aoff + m * 2048 + k * 1024); } while (0)
; #define PG8_LDB(dst, b, h) do { _Pragma("unroll") for (int n = 0; n < 2; ++n) _Pragma("unroll") for (int k = 0; k < 2; ++k) dst[n][k] = *(const PG8_LAS bf16x8*)(lds + PG8_SB(b, h) + boff + n * 2048 + k * 1024); } while (0)
; #define PG8_MMA(ai, bj, At, Bt) do { __builtin_amdgcn_s_setprio(1); _Pragma("unroll") for (int m = 0; m < 4; ++m) _Pragma("unroll") for (int n = 0; n < 2; ++n) _Pragma("unroll") for (int k = 0; k < 2; ++k) \
;         acc[ai][bj][m][n] = __builtin_amdgcn_mfma_f32_16x16x32_bf16(Bt[n][k], At[m][k], acc[ai][bj][m][n], 0, 0, 0); __builtin_amdgcn_s_setprio(0); } while (0)
; #define PG8_WAIT_V(n) asm volatile("s_waitcnt vmcnt(" #n ")" ::: "memory")
; #define PG8_WAIT_L(n) asm volatile("s_waitcnt lgkmcnt(" #n ")" ::: "memory")
; #define PG8_BAR __builtin_amdgcn_s_barrier()
; #define PG8_SCHED __builtin_amdgcn_sched_barrier(0)
; template <class Epi, class Sched, bool ALIGN_EPI = false, bool SP2 = false>
; __device__ __forceinline__ void gemm_phase(PG8_LAS unsigned char* lds, const Gemm g, const Sched& S, const Epi& E) {
;     ...
;             PG8_LDB(B0, 0, 0); PG8_LDB(B1, 0, 1); PG8_SCHED; PG8_LDA(At, 0, 0); PG8_STAGE(PG8_SA(1, 1), a1 + hstep, voffA);
;             PG8_WAIT_V(8); PG8_WAIT_L(0); PG8_BAR; PG8_MMA(0, 0, At, B0); PG8_MMA(0, 1, At, B1); PG8_BAR; PG8_SCHED;
;             PG8_LDA(At, 0, 1); PG8_STAGE(PG8_SB(0, 0), b2, voffB); PG8_STAGE(PG8_SB(0, 1), b2 + hstep, voffB); PG8_STAGE(PG8_SA(0, 0), a2, voffA);
;             PG8_WAIT_V(8); PG8_WAIT_L(0); PG8_BAR; PG8_MMA(1, 0, At, B0); PG8_MMA(1, 1, At, B1); PG8_BAR; PG8_SCHED;
.Lsp_1:
.LBB0_164:
	s_add_u32 s58, s72, 0xfffc0080
	s_addc_u32 s59, s73, -1
	s_add_i32 s84, 0, 0x10000
	s_cmp_eq_u32 s94, 12
	s_cselect_b32 s65, s36, s59
	s_cselect_b32 s64, s37, s58
	v_add_u32_e32 v140, s84, v146
	s_cselect_b32 s59, s51, s93
	s_cselect_b32 s58, s53, s92
	s_add_i32 s96, 0, 0x14000
	ds_read_b128 v[142:145], v140
	ds_read_b128 v[150:153], v140 offset:1024
	ds_read_b128 v[154:157], v140 offset:2048
	ds_read_b128 v[158:161], v140 offset:3072
	v_add_u32_e32 v140, s96, v146
	ds_read_b128 v[162:165], v140
	ds_read_b128 v[166:169], v140 offset:1024
	ds_read_b128 v[170:173], v140 offset:2048
	ds_read_b128 v[174:177], v140 offset:3072
	v_lshl_add_u64 v[186:187], s[72:73], 0, v[136:137]
	s_add_i32 m0, s19, 0xc000
	ds_read_b128 v[178:181], v148
	ds_read_b128 v[182:185], v148 offset:1024
	ds_read_b128 v[190:193], v148 offset:2048
	ds_read_b128 v[194:197], v148 offset:3072
	ds_read_b128 v[198:201], v148 offset:4096
	ds_read_b128 v[202:205], v148 offset:5120
	ds_read_b128 v[206:209], v148 offset:6144
	ds_read_b128 v[228:231], v148 offset:7168
	global_load_lds_dwordx4 v[186:187], off
	v_lshl_add_u64 v[186:187], s[72:73], 0, v[138:139]
	s_add_i32 m0, s19, 0xe000
	s_nop 0
	global_load_lds_dwordx4 v[186:187], off
	s_waitcnt vmcnt(8)
	s_waitcnt lgkmcnt(0)
	s_barrier
	s_waitcnt lgkmcnt(0)
	v_mfma_f32_16x16x32_bf16 v[124:127], v[142:145], v[178:181], v[124:127]
	v_mfma_f32_16x16x32_bf16 v[120:123], v[154:157], v[178:181], v[120:123]
	v_mfma_f32_16x16x32_bf16 v[116:119], v[142:145], v[190:193], v[116:119]
	v_mfma_f32_16x16x32_bf16 v[112:115], v[154:157], v[190:193], v[112:115]
	v_mfma_f32_16x16x32_bf16 v[108:111], v[142:145], v[198:201], v[108:111]
	v_mfma_f32_16x16x32_bf16 v[104:107], v[154:157], v[198:201], v[104:107]
	v_mfma_f32_16x16x32_bf16 v[100:103], v[142:145], v[206:209], v[100:103]
	v_mfma_f32_16x16x32_bf16 v[96:99], v[154:157], v[206:209], v[96:99]
	v_mfma_f32_16x16x32_bf16 v[124:127], v[150:153], v[182:185], v[124:127]
	v_mfma_f32_16x16x32_bf16 v[120:123], v[158:161], v[182:185], v[120:123]
	v_mfma_f32_16x16x32_bf16 v[116:119], v[150:153], v[194:197], v[116:119]
	v_mfma_f32_16x16x32_bf16 v[112:115], v[158:161], v[194:197], v[112:115]
	v_mfma_f32_16x16x32_bf16 v[108:111], v[150:153], v[202:205], v[108:111]
	v_mfma_f32_16x16x32_bf16 v[104:107], v[158:161], v[202:205], v[104:107]
	v_mfma_f32_16x16x32_bf16 v[100:103], v[150:153], v[228:231], v[100:103]
	v_mfma_f32_16x16x32_bf16 v[96:99], v[158:161], v[228:231], v[96:99]
	v_mfma_f32_16x16x32_bf16 v[92:95], v[162:165], v[178:181], v[92:95]
	v_mfma_f32_16x16x32_bf16 v[88:91], v[170:173], v[178:181], v[88:91]
	v_mfma_f32_16x16x32_bf16 v[84:87], v[162:165], v[190:193], v[84:87]
	v_mfma_f32_16x16x32_bf16 v[80:83], v[170:173], v[190:193], v[80:83]
	v_mfma_f32_16x16x32_bf16 v[76:79], v[162:165], v[198:201], v[76:79]
	v_mfma_f32_16x16x32_bf16 v[72:75], v[170:173], v[198:201], v[72:75]
	v_mfma_f32_16x16x32_bf16 v[68:71], v[162:165], v[206:209], v[68:71]
	v_mfma_f32_16x16x32_bf16 v[64:67], v[170:173], v[206:209], v[64:67]
	v_mfma_f32_16x16x32_bf16 v[92:95], v[166:169], v[182:185], v[92:95]
	v_mfma_f32_16x16x32_bf16 v[88:91], v[174:177], v[182:185], v[88:91]
	v_mfma_f32_16x16x32_bf16 v[84:87], v[166:169], v[194:197], v[84:87]
	v_mfma_f32_16x16x32_bf16 v[80:83], v[174:177], v[194:197], v[80:83]
	v_mfma_f32_16x16x32_bf16 v[76:79], v[166:169], v[202:205], v[76:79]
	v_mfma_f32_16x16x32_bf16 v[72:75], v[174:177], v[202:205], v[72:75]
	v_mfma_f32_16x16x32_bf16 v[68:71], v[166:169], v[228:231], v[68:71]
	v_mfma_f32_16x16x32_bf16 v[64:67], v[174:177], v[228:231], v[64:67]
	s_barrier
	s_add_i32 s84, s84, s18
	v_lshl_add_u64 v[186:187], s[58:59], 0, v[128:129]
	s_mov_b32 m0, s84
	ds_read_b128 v[178:181], v148 offset:16384
	ds_read_b128 v[182:185], v148 offset:17408
	ds_read_b128 v[190:193], v148 offset:18432
	ds_read_b128 v[194:197], v148 offset:19456
	ds_read_b128 v[198:201], v148 offset:20480
	ds_read_b128 v[202:205], v148 offset:21504
	ds_read_b128 v[206:209], v148 offset:22528
	ds_read_b128 v[228:231], v148 offset:23552
	global_load_lds_dwordx4 v[186:187], off
	s_add_i32 m0, s84, 0x2000
	s_add_u32 s84, s58, 0x40000
	v_lshl_add_u64 v[188:189], s[58:59], 0, v[130:131]
	s_addc_u32 s85, s59, 0
	s_add_i32 s96, s96, s18
	global_load_lds_dwordx4 v[188:189], off
	v_lshl_add_u64 v[210:211], s[84:85], 0, v[128:129]
	s_mov_b32 m0, s96
	v_lshl_add_u64 v[232:233], s[64:65], 0, v[132:133]
	global_load_lds_dwordx4 v[210:211], off
	v_lshl_add_u64 v[210:211], s[84:85], 0, v[130:131]
	s_add_i32 m0, s96, 0x2000
	s_nop 0
	global_load_lds_dwordx4 v[210:211], off
	v_lshl_add_u64 v[210:211], s[64:65], 0, v[134:135]
	s_mov_b32 m0, s19
	s_nop 0
	global_load_lds_dwordx4 v[210:211], off
	s_mov_b32 m0, s20
	s_nop 0
	global_load_lds_dwordx4 v[232:233], off
	s_nop 0
	s_waitcnt vmcnt(8)
	s_waitcnt lgkmcnt(0)
	s_barrier
; #define PG8_STAGE(bufoff, gbase, voff) do { _Pragma("unroll") for (int _i = 0; _i < 2; ++_i) \
;         __builtin_amdgcn_global_load_lds((const unsigned*)((const char*)(gbase) + (voff)[_i]), (PG8_LAS unsigned*)(lds + (bufoff) + ldsw + _i * 8192), 16, 0, 0); } while (0)
; #define PG8_LDA(dst, b, h) do { _Pragma("unroll") for (int m = 0; m < 4; ++m) _Pragma("unroll") for (int k = 0; k < 2; ++k) dst[m][k] = *(const PG8_LAS bf16x8*)(lds + PG8_SA(b, h) + aoff + m * 2048 + k * 1024); } while (0)
; #define PG8_LDB(dst, b, h) do { _Pragma("unroll") for (int n = 0; n < 2; ++n) _Pragma("unroll") for (int k = 0; k < 2; ++k) dst[n][k] = *(const PG8_LAS bf16x8*)(lds + PG8_SB(b, h) + boff + n * 2048 + k * 1024); } while (0)
; #define PG8_MMA(ai, bj, At, Bt) do { __builtin_amdgcn_s_setprio(1); _Pragma("unroll") for (int m = 0; m < 4; ++m) _Pragma("unroll") for (int n = 0; n < 2; ++n) _Pragma("unroll") for (int k = 0; k < 2; ++k) \
;         acc[ai][bj][m][n] = __builtin_amdgcn_mfma_f32_16x16x32_bf16(Bt[n][k], At[m][k], acc[ai][bj][m][n], 0, 0, 0); __builtin_amdgcn_s_setprio(0); } while (0)
; #define PG8_WAIT_V(n) asm volatile("s_waitcnt vmcnt(" #n ")" ::: "memory")
; #define PG8_WAIT_L(n) asm volatile("s_waitcnt lgkmcnt(" #n ")" ::: "memory")
; #define PG8_BAR __builtin_amdgcn_s_barrier()
; #define PG8_SCHED __builtin_amdgcn_sched_barrier(0)
; template <class Epi, class Sched, bool ALIGN_EPI = false, bool SP2 = false>
; __device__ __forceinline__ void gemm_phase(PG8_LAS unsigned char* lds, const Gemm g, const Sched& S, const Epi& E) {
;     ...
;             PG8_LDA(At, 0, 1); PG8_STAGE(PG8_SB(0, 0), b2, voffB); PG8_STAGE(PG8_SB(0, 1), b2 + hstep, voffB); PG8_STAGE(PG8_SA(0, 0), a2, voffA);
;             PG8_WAIT_V(8); PG8_WAIT_L(0); PG8_BAR; PG8_MMA(1, 0, At, B0); PG8_MMA(1, 1, At, B1); PG8_BAR; PG8_SCHED;
;             PG8_LDB(B0, 1, 0); PG8_LDB(B1, 1, 1); PG8_SCHED; PG8_LDA(At, 1, 0); PG8_STAGE(PG8_SA(0, 1), a2 + hstep, voffA);
;             PG8_WAIT_V(8); PG8_WAIT_L(0); PG8_BAR; PG8_MMA(0, 0, At, B0); PG8_MMA(0, 1, At, B1); PG8_BAR; PG8_SCHED;
	s_waitcnt lgkmcnt(0)
	v_mfma_f32_16x16x32_bf16 v[60:63], v[142:145], v[178:181], v[60:63]
	v_mfma_f32_16x16x32_bf16 v[56:59], v[154:157], v[178:181], v[56:59]
	v_mfma_f32_16x16x32_bf16 v[52:55], v[142:145], v[190:193], v[52:55]
	v_mfma_f32_16x16x32_bf16 v[48:51], v[154:157], v[190:193], v[48:51]
	v_mfma_f32_16x16x32_bf16 v[44:47], v[142:145], v[198:201], v[44:47]
	v_mfma_f32_16x16x32_bf16 v[40:43], v[154:157], v[198:201], v[40:43]
	v_mfma_f32_16x16x32_bf16 v[36:39], v[142:145], v[206:209], v[36:39]
	v_mfma_f32_16x16x32_bf16 v[32:35], v[154:157], v[206:209], v[32:35]
	v_mfma_f32_16x16x32_bf16 v[60:63], v[150:153], v[182:185], v[60:63]
	v_mfma_f32_16x16x32_bf16 v[56:59], v[158:161], v[182:185], v[56:59]
	v_mfma_f32_16x16x32_bf16 v[52:55], v[150:153], v[194:197], v[52:55]
	v_mfma_f32_16x16x32_bf16 v[48:51], v[158:161], v[194:197], v[48:51]
	v_mfma_f32_16x16x32_bf16 v[44:47], v[150:153], v[202:205], v[44:47]
	v_mfma_f32_16x16x32_bf16 v[40:43], v[158:161], v[202:205], v[40:43]
	v_mfma_f32_16x16x32_bf16 v[36:39], v[150:153], v[228:231], v[36:39]
	v_mfma_f32_16x16x32_bf16 v[32:35], v[158:161], v[228:231], v[32:35]
	v_mfma_f32_16x16x32_bf16 v[28:31], v[162:165], v[178:181], v[28:31]
	v_mfma_f32_16x16x32_bf16 v[24:27], v[170:173], v[178:181], v[24:27]
	v_mfma_f32_16x16x32_bf16 v[20:23], v[162:165], v[190:193], v[20:23]
	v_mfma_f32_16x16x32_bf16 v[16:19], v[170:173], v[190:193], v[16:19]
	v_mfma_f32_16x16x32_bf16 v[12:15], v[162:165], v[198:201], v[12:15]
	v_mfma_f32_16x16x32_bf16 v[8:11], v[170:173], v[198:201], v[8:11]
	v_mfma_f32_16x16x32_bf16 v[4:7], v[162:165], v[206:209], v[4:7]
	v_mfma_f32_16x16x32_bf16 v[0:3], v[170:173], v[206:209], v[0:3]
	v_mfma_f32_16x16x32_bf16 v[28:31], v[166:169], v[182:185], v[28:31]
	v_mfma_f32_16x16x32_bf16 v[24:27], v[174:177], v[182:185], v[24:27]
	v_mfma_f32_16x16x32_bf16 v[20:23], v[166:169], v[194:197], v[20:23]
	v_mfma_f32_16x16x32_bf16 v[16:19], v[174:177], v[194:197], v[16:19]
	v_mfma_f32_16x16x32_bf16 v[12:15], v[166:169], v[202:205], v[12:15]
	v_mfma_f32_16x16x32_bf16 v[8:11], v[174:177], v[202:205], v[8:11]
	v_mfma_f32_16x16x32_bf16 v[4:7], v[166:169], v[228:231], v[4:7]
	v_mfma_f32_16x16x32_bf16 v[0:3], v[174:177], v[228:231], v[0:3]
	s_barrier
	s_add_i32 s84, 0, 0x18000
	v_add_u32_e32 v140, s84, v146
	s_add_i32 s85, 0, 0x1c000
	ds_read_b128 v[142:145], v140
	ds_read_b128 v[150:153], v140 offset:1024
	ds_read_b128 v[154:157], v140 offset:2048
	ds_read_b128 v[158:161], v140 offset:3072
	v_add_u32_e32 v140, s85, v146
	ds_read_b128 v[162:165], v140
	ds_read_b128 v[166:169], v140 offset:1024
	ds_read_b128 v[170:173], v140 offset:2048
	ds_read_b128 v[174:177], v140 offset:3072
	s_add_u32 s64, s64, 0x40000
	s_addc_u32 s65, s65, 0
	s_mov_b32 m0, s21
	v_lshl_add_u64 v[234:235], s[64:65], 0, v[134:135]
	ds_read_b128 v[178:181], v148 offset:32768
	ds_read_b128 v[182:185], v148 offset:33792
	ds_read_b128 v[190:193], v148 offset:34816
	ds_read_b128 v[194:197], v148 offset:35840
	ds_read_b128 v[198:201], v148 offset:36864
	ds_read_b128 v[202:205], v148 offset:37888
	ds_read_b128 v[206:209], v148 offset:38912
	ds_read_b128 v[228:231], v148 offset:39936
	global_load_lds_dwordx4 v[234:235], off
	v_lshl_add_u64 v[234:235], s[64:65], 0, v[132:133]
	s_mov_b32 m0, s22
	s_nop 0
	global_load_lds_dwordx4 v[234:235], off
	s_nop 0
	s_waitcnt vmcnt(8)
	s_waitcnt lgkmcnt(0)
	s_barrier
	s_waitcnt lgkmcnt(0)
	v_mfma_f32_16x16x32_bf16 v[124:127], v[142:145], v[178:181], v[124:127]
	v_mfma_f32_16x16x32_bf16 v[120:123], v[154:157], v[178:181], v[120:123]
	v_mfma_f32_16x16x32_bf16 v[116:119], v[142:145], v[190:193], v[116:119]
	v_mfma_f32_16x16x32_bf16 v[112:115], v[154:157], v[190:193], v[112:115]
	v_mfma_f32_16x16x32_bf16 v[108:111], v[142:145], v[198:201], v[108:111]
	v_mfma_f32_16x16x32_bf16 v[104:107], v[154:157], v[198:201], v[104:107]
	v_mfma_f32_16x16x32_bf16 v[100:103], v[142:145], v[206:209], v[100:103]
	v_mfma_f32_16x16x32_bf16 v[96:99], v[154:157], v[206:209], v[96:99]
	v_mfma_f32_16x16x32_bf16 v[124:127], v[150:153], v[182:185], v[124:127]
	v_mfma_f32_16x16x32_bf16 v[120:123], v[158:161], v[182:185], v[120:123]
	v_mfma_f32_16x16x32_bf16 v[116:119], v[150:153], v[194:197], v[116:119]
	v_mfma_f32_16x16x32_bf16 v[112:115], v[158:161], v[194:197], v[112:115]
	v_mfma_f32_16x16x32_bf16 v[108:111], v[150:153], v[202:205], v[108:111]
	v_mfma_f32_16x16x32_bf16 v[104:107], v[158:161], v[202:205], v[104:107]
	v_mfma_f32_16x16x32_bf16 v[100:103], v[150:153], v[228:231], v[100:103]
	v_mfma_f32_16x16x32_bf16 v[96:99], v[158:161], v[228:231], v[96:99]
	v_mfma_f32_16x16x32_bf16 v[92:95], v[162:165], v[178:181], v[92:95]
	v_mfma_f32_16x16x32_bf16 v[88:91], v[170:173], v[178:181], v[88:91]
	v_mfma_f32_16x16x32_bf16 v[84:87], v[162:165], v[190:193], v[84:87]
	v_mfma_f32_16x16x32_bf16 v[80:83], v[170:173], v[190:193], v[80:83]
	v_mfma_f32_16x16x32_bf16 v[76:79], v[162:165], v[198:201], v[76:79]
	v_mfma_f32_16x16x32_bf16 v[72:75], v[170:173], v[198:201], v[72:75]
	v_mfma_f32_16x16x32_bf16 v[68:71], v[162:165], v[206:209], v[68:71]
	v_mfma_f32_16x16x32_bf16 v[64:67], v[170:173], v[206:209], v[64:67]
	v_mfma_f32_16x16x32_bf16 v[92:95], v[166:169], v[182:185], v[92:95]
	v_mfma_f32_16x16x32_bf16 v[88:91], v[174:177], v[182:185], v[88:91]
	v_mfma_f32_16x16x32_bf16 v[84:87], v[166:169], v[194:197], v[84:87]
	v_mfma_f32_16x16x32_bf16 v[80:83], v[174:177], v[194:197], v[80:83]
	v_mfma_f32_16x16x32_bf16 v[76:79], v[166:169], v[202:205], v[76:79]
	v_mfma_f32_16x16x32_bf16 v[72:75], v[174:177], v[202:205], v[72:75]
	v_mfma_f32_16x16x32_bf16 v[68:71], v[166:169], v[228:231], v[68:71]
	v_mfma_f32_16x16x32_bf16 v[64:67], v[174:177], v[228:231], v[64:67]
	s_barrier
; #define PG8_STAGE(bufoff, gbase, voff) do { _Pragma("unroll") for (int _i = 0; _i < 2; ++_i) \
;         __builtin_amdgcn_global_load_lds((const unsigned*)((const char*)(gbase) + (voff)[_i]), (PG8_LAS unsigned*)(lds + (bufoff) + ldsw + _i * 8192), 16, 0, 0); } while (0)
; #define PG8_LDA(dst, b, h) do { _Pragma("unroll") for (int m = 0; m < 4; ++m) _Pragma("unroll") for (int k = 0; k < 2; ++k) dst[m][k] = *(const PG8_LAS bf16x8*)(lds + PG8_SA(b, h) + aoff + m * 2048 + k * 1024); } while (0)
; #define PG8_MMA(ai, bj, At, Bt) do { __builtin_amdgcn_s_setprio(1); _Pragma("unroll") for (int m = 0; m < 4; ++m) _Pragma("unroll") for (int n = 0; n < 2; ++n) _Pragma("unroll") for (int k = 0; k < 2; ++k) \
;         acc[ai][bj][m][n] = __builtin_amdgcn_mfma_f32_16x16x32_bf16(Bt[n][k], At[m][k], acc[ai][bj][m][n], 0, 0, 0); __builtin_amdgcn_s_setprio(0); } while (0)
; #define PG8_WAIT_V(n) asm volatile("s_waitcnt vmcnt(" #n ")" ::: "memory")
; #define PG8_WAIT_L(n) asm volatile("s_waitcnt lgkmcnt(" #n ")" ::: "memory")
; #define PG8_BAR __builtin_amdgcn_s_barrier()
; #define PG8_SCHED __builtin_amdgcn_sched_barrier(0)
; template <class Epi, class Sched, bool ALIGN_EPI = false, bool SP2 = false>
; __device__ __forceinline__ void gemm_phase(PG8_LAS unsigned char* lds, const Gemm g, const Sched& S, const Epi& E) {
;     ...
;         for (int t = 0; t < nt; t += 2) {
;             const bool last = (t == nt - 2);
;             const char* a1 = cA + (size_t)(t + 1) * kstep;
;             const char* a2 = last ? nA : cA + (size_t)(t + 2) * kstep; const char* b2 = last ? nB : cB + (size_t)(t + 2) * kstep;
;             const char* a3 = a2 + kstep; const char* b3 = b2 + kstep;
;     ...
;             PG8_LDA(At, 1, 1); PG8_STAGE(PG8_SB(1, 0), b3, voffB); PG8_STAGE(PG8_SB(1, 1), b3 + hstep, voffB); PG8_STAGE(PG8_SA(1, 0), a3, voffA);
;             PG8_WAIT_V(8); PG8_WAIT_L(0); PG8_BAR; PG8_MMA(1, 0, At, B0); PG8_MMA(1, 1, At, B1); PG8_BAR; PG8_SCHED;
	s_add_i32 s64, s84, s18
	v_lshl_add_u64 v[186:187], v[186:187], 0, s[90:91]
	s_mov_b32 m0, s64
	ds_read_b128 v[178:181], v148 offset:49152
	ds_read_b128 v[182:185], v148 offset:50176
	ds_read_b128 v[190:193], v148 offset:51200
	ds_read_b128 v[194:197], v148 offset:52224
	ds_read_b128 v[198:201], v148 offset:53248
	ds_read_b128 v[202:205], v148 offset:54272
	ds_read_b128 v[206:209], v148 offset:55296
	ds_read_b128 v[228:231], v148 offset:56320
	global_load_lds_dwordx4 v[186:187], off
	s_add_i32 m0, s64, 0x2000
	s_add_u32 s58, s58, 0x40080
	v_lshl_add_u64 v[186:187], v[188:189], 0, s[90:91]
	s_addc_u32 s59, s59, 0
	s_add_i32 s64, s85, s18
	global_load_lds_dwordx4 v[186:187], off
	v_lshl_add_u64 v[186:187], s[58:59], 0, v[128:129]
	s_mov_b32 m0, s64
	s_nop 0
	global_load_lds_dwordx4 v[186:187], off
	v_lshl_add_u64 v[186:187], s[58:59], 0, v[130:131]
	s_add_i32 m0, s64, 0x2000
	s_nop 0
	global_load_lds_dwordx4 v[186:187], off
	v_lshl_add_u64 v[186:187], v[210:211], 0, s[90:91]
	s_mov_b32 m0, s28
	s_nop 0
	global_load_lds_dwordx4 v[186:187], off
	v_lshl_add_u64 v[186:187], v[232:233], 0, s[90:91]
	s_mov_b32 m0, s29
	s_nop 0
	global_load_lds_dwordx4 v[186:187], off
	s_waitcnt vmcnt(8)
	s_waitcnt lgkmcnt(0)
	s_barrier
	s_waitcnt lgkmcnt(0)
	v_mfma_f32_16x16x32_bf16 v[60:63], v[142:145], v[178:181], v[60:63]
	v_mfma_f32_16x16x32_bf16 v[56:59], v[154:157], v[178:181], v[56:59]
	v_mfma_f32_16x16x32_bf16 v[52:55], v[142:145], v[190:193], v[52:55]
	v_mfma_f32_16x16x32_bf16 v[48:51], v[154:157], v[190:193], v[48:51]
	v_mfma_f32_16x16x32_bf16 v[44:47], v[142:145], v[198:201], v[44:47]
	v_mfma_f32_16x16x32_bf16 v[40:43], v[154:157], v[198:201], v[40:43]
	v_mfma_f32_16x16x32_bf16 v[36:39], v[142:145], v[206:209], v[36:39]
	v_mfma_f32_16x16x32_bf16 v[32:35], v[154:157], v[206:209], v[32:35]
	v_mfma_f32_16x16x32_bf16 v[60:63], v[150:153], v[182:185], v[60:63]
	v_mfma_f32_16x16x32_bf16 v[56:59], v[158:161], v[182:185], v[56:59]
	v_mfma_f32_16x16x32_bf16 v[52:55], v[150:153], v[194:197], v[52:55]
	v_mfma_f32_16x16x32_bf16 v[48:51], v[158:161], v[194:197], v[48:51]
	v_mfma_f32_16x16x32_bf16 v[44:47], v[150:153], v[202:205], v[44:47]
	v_mfma_f32_16x16x32_bf16 v[40:43], v[158:161], v[202:205], v[40:43]
	v_mfma_f32_16x16x32_bf16 v[36:39], v[150:153], v[228:231], v[36:39]
	v_mfma_f32_16x16x32_bf16 v[32:35], v[158:161], v[228:231], v[32:35]
	v_mfma_f32_16x16x32_bf16 v[28:31], v[162:165], v[178:181], v[28:31]
	v_mfma_f32_16x16x32_bf16 v[24:27], v[170:173], v[178:181], v[24:27]
	v_mfma_f32_16x16x32_bf16 v[20:23], v[162:165], v[190:193], v[20:23]
	v_mfma_f32_16x16x32_bf16 v[16:19], v[170:173], v[190:193], v[16:19]
	v_mfma_f32_16x16x32_bf16 v[12:15], v[162:165], v[198:201], v[12:15]
	v_mfma_f32_16x16x32_bf16 v[8:11], v[170:173], v[198:201], v[8:11]
	v_mfma_f32_16x16x32_bf16 v[4:7], v[162:165], v[206:209], v[4:7]
	v_mfma_f32_16x16x32_bf16 v[0:3], v[170:173], v[206:209], v[0:3]
	v_mfma_f32_16x16x32_bf16 v[28:31], v[166:169], v[182:185], v[28:31]
	v_mfma_f32_16x16x32_bf16 v[24:27], v[174:177], v[182:185], v[24:27]
	v_mfma_f32_16x16x32_bf16 v[20:23], v[166:169], v[194:197], v[20:23]
	v_mfma_f32_16x16x32_bf16 v[16:19], v[174:177], v[194:197], v[16:19]
	v_mfma_f32_16x16x32_bf16 v[12:15], v[166:169], v[202:205], v[12:15]
	v_mfma_f32_16x16x32_bf16 v[8:11], v[174:177], v[202:205], v[8:11]
	v_mfma_f32_16x16x32_bf16 v[4:7], v[166:169], v[228:231], v[4:7]
	v_mfma_f32_16x16x32_bf16 v[0:3], v[174:177], v[228:231], v[0:3]
	s_barrier
	s_add_i32 s94, s94, 2
	s_add_u32 s72, s72, 0x100
	s_addc_u32 s73, s73, 0
	s_add_u32 s92, s92, 0x100
	s_addc_u32 s93, s93, 0
	s_cmp_gt_u32 s94, 13
	s_cbranch_scc0 .LBB0_164
	s_setprio 0
	s_and_b64 vcc, exec, s[48:49]
	s_cbranch_vccz .LBB0_167
	s_barrier

; #define PG8_STAGE(bufoff, gbase, voff) do { _Pragma("unroll") for (int _i = 0; _i < 2; ++_i) \
;         __builtin_amdgcn_global_load_lds((const unsigned*)((const char*)(gbase) + (voff)[_i]), (PG8_LAS unsigned*)(lds + (bufoff) + ldsw + _i * 8192), 16, 0, 0); } while (0)
; #define PG8_LDA(dst, b, h) do { _Pragma("unroll") for (int m = 0; m < 4; ++m) _Pragma("unroll") for (int k = 0; k < 2; ++k) dst[m][k] = *(const PG8_LAS bf16x8*)(lds + PG8_SA(b, h) + aoff + m * 2048 + k * 1024); } while (0)
; #define PG8_LDB(dst, b, h) do { _Pragma("unroll") for (int n = 0; n < 2; ++n) _Pragma("unroll") for (int k = 0; k < 2; ++k) dst[n][k] = *(const PG8_LAS bf16x8*)(lds + PG8_SB(b, h) + boff + n * 2048 + k * 1024); } while (0)
; #define PG8_MMA(ai, bj, At, Bt) do { __builtin_amdgcn_s_setprio(1); _Pragma("unroll") for (int m = 0; m < 4; ++m) _Pragma("unroll") for (int n = 0; n < 2; ++n) _Pragma("unroll") for (int k = 0; k < 2; ++k) \
;         acc[ai][bj][m][n] = __builtin_amdgcn_mfma_f32_16x16x32_bf16(Bt[n][k], At[m][k], acc[ai][bj][m][n], 0, 0, 0); __builtin_amdgcn_s_setprio(0); } while (0)
; #define PG8_WAIT_V(n) asm volatile("s_waitcnt vmcnt(" #n ")" ::: "memory")
; #define PG8_WAIT_L(n) asm volatile("s_waitcnt lgkmcnt(" #n ")" ::: "memory")
; #define PG8_BAR __builtin_amdgcn_s_barrier()
; #define PG8_SCHED __builtin_amdgcn_sched_barrier(0)
; template <class Epi, class Sched, bool ALIGN_EPI = false, bool SP2 = false>
; __device__ __forceinline__ void gemm_phase(PG8_LAS unsigned char* lds, const Gemm g, const Sched& S, const Epi& E) {
;     ...
;             PG8_LDB(B0, 0, 0); PG8_LDB(B1, 0, 1); PG8_SCHED; PG8_LDA(At, 0, 0); PG8_STAGE(PG8_SA(1, 1), a1 + hstep, voffA);
;             PG8_WAIT_V(8); PG8_WAIT_L(0); PG8_BAR; PG8_MMA(0, 0, At, B0); PG8_MMA(0, 1, At, B1); PG8_BAR; PG8_SCHED;
;             PG8_LDA(At, 0, 1); PG8_STAGE(PG8_SB(0, 0), b2, voffB); PG8_STAGE(PG8_SB(0, 1), b2 + hstep, voffB); PG8_STAGE(PG8_SA(0, 0), a2, voffA);
;             PG8_WAIT_V(8); PG8_WAIT_L(0); PG8_BAR; PG8_MMA(1, 0, At, B0); PG8_MMA(1, 1, At, B1); PG8_BAR; PG8_SCHED;
.Lsp_2:
.LBB0_564:
	s_add_u32 s44, vcc_lo, 0xfffc0080
	s_addc_u32 s45, vcc_hi, -1
	s_add_i32 s85, 0, 0x10000
	s_cmp_eq_u32 s84, 12
	s_cselect_b32 s93, s36, s45
	s_cselect_b32 s92, s37, s44
	s_cselect_b32 s59, s67, s94
	s_cselect_b32 s58, s73, s88
	s_add_i32 s8, 0, 0x14000
	v_add_u32_e32 v142, s85, v201
	v_add_u32_e32 v168, s8, v201
	ds_read_b128 v[130:133], v142
	ds_read_b128 v[134:137], v142 offset:1024
	ds_read_b128 v[138:141], v142 offset:2048
	ds_read_b128 v[142:145], v142 offset:3072
	ds_read_b128 v[156:159], v168
	ds_read_b128 v[160:163], v168 offset:1024
	ds_read_b128 v[164:167], v168 offset:2048
	ds_read_b128 v[168:171], v168 offset:3072
	v_lshl_add_u64 v[208:209], vcc, 0, v[152:153]
	s_add_i32 m0, s15, 0xc000
	ds_read_b128 v[172:175], v203
	ds_read_b128 v[176:179], v203 offset:1024
	ds_read_b128 v[180:183], v203 offset:2048
	ds_read_b128 v[184:187], v203 offset:3072
	ds_read_b128 v[188:191], v203 offset:4096
	ds_read_b128 v[192:195], v203 offset:5120
	ds_read_b128 v[196:199], v203 offset:6144
	ds_read_b128 v[204:207], v203 offset:7168
	global_load_lds_dwordx4 v[208:209], off
	v_lshl_add_u64 v[208:209], vcc, 0, v[154:155]
	s_add_i32 m0, s15, 0xe000
	s_nop 0
	global_load_lds_dwordx4 v[208:209], off
	s_nop 0
	s_waitcnt vmcnt(8)
	s_waitcnt lgkmcnt(0)
	s_barrier
	s_waitcnt lgkmcnt(0)
	v_mfma_f32_16x16x32_bf16 v[124:127], v[130:133], v[172:175], v[124:127]
	v_mfma_f32_16x16x32_bf16 v[120:123], v[138:141], v[172:175], v[120:123]
	v_mfma_f32_16x16x32_bf16 v[108:111], v[130:133], v[180:183], v[108:111]
	v_mfma_f32_16x16x32_bf16 v[104:107], v[138:141], v[180:183], v[104:107]
	v_mfma_f32_16x16x32_bf16 v[92:95], v[130:133], v[188:191], v[92:95]
	v_mfma_f32_16x16x32_bf16 v[88:91], v[138:141], v[188:191], v[88:91]
	v_mfma_f32_16x16x32_bf16 v[76:79], v[130:133], v[196:199], v[76:79]
	v_mfma_f32_16x16x32_bf16 v[72:75], v[138:141], v[196:199], v[72:75]
	v_mfma_f32_16x16x32_bf16 v[124:127], v[134:137], v[176:179], v[124:127]
	v_mfma_f32_16x16x32_bf16 v[120:123], v[142:145], v[176:179], v[120:123]
	v_mfma_f32_16x16x32_bf16 v[108:111], v[134:137], v[184:187], v[108:111]
	v_mfma_f32_16x16x32_bf16 v[104:107], v[142:145], v[184:187], v[104:107]
	v_mfma_f32_16x16x32_bf16 v[92:95], v[134:137], v[192:195], v[92:95]
	v_mfma_f32_16x16x32_bf16 v[88:91], v[142:145], v[192:195], v[88:91]
	v_mfma_f32_16x16x32_bf16 v[76:79], v[134:137], v[204:207], v[76:79]
	v_mfma_f32_16x16x32_bf16 v[72:75], v[142:145], v[204:207], v[72:75]
	v_mfma_f32_16x16x32_bf16 v[116:119], v[156:159], v[172:175], v[116:119]
	v_mfma_f32_16x16x32_bf16 v[112:115], v[164:167], v[172:175], v[112:115]
	v_mfma_f32_16x16x32_bf16 v[100:103], v[156:159], v[180:183], v[100:103]
	v_mfma_f32_16x16x32_bf16 v[96:99], v[164:167], v[180:183], v[96:99]
	v_mfma_f32_16x16x32_bf16 v[84:87], v[156:159], v[188:191], v[84:87]
	v_mfma_f32_16x16x32_bf16 v[80:83], v[164:167], v[188:191], v[80:83]
	v_mfma_f32_16x16x32_bf16 v[68:71], v[156:159], v[196:199], v[68:71]
	v_mfma_f32_16x16x32_bf16 v[64:67], v[164:167], v[196:199], v[64:67]
	v_mfma_f32_16x16x32_bf16 v[116:119], v[160:163], v[176:179], v[116:119]
	v_mfma_f32_16x16x32_bf16 v[112:115], v[168:171], v[176:179], v[112:115]
	v_mfma_f32_16x16x32_bf16 v[100:103], v[160:163], v[184:187], v[100:103]
	v_mfma_f32_16x16x32_bf16 v[96:99], v[168:171], v[184:187], v[96:99]
	v_mfma_f32_16x16x32_bf16 v[84:87], v[160:163], v[192:195], v[84:87]
	v_mfma_f32_16x16x32_bf16 v[80:83], v[168:171], v[192:195], v[80:83]
	v_mfma_f32_16x16x32_bf16 v[68:71], v[160:163], v[204:207], v[68:71]
	v_mfma_f32_16x16x32_bf16 v[64:67], v[168:171], v[204:207], v[64:67]
	s_barrier
	s_add_i32 s44, s85, s14
	v_lshl_add_u64 v[208:209], s[58:59], 0, v[128:129]
	s_mov_b32 m0, s44
	ds_read_b128 v[172:175], v203 offset:16384
	ds_read_b128 v[176:179], v203 offset:17408
	ds_read_b128 v[180:183], v203 offset:18432
	ds_read_b128 v[184:187], v203 offset:19456
	ds_read_b128 v[188:191], v203 offset:20480
	ds_read_b128 v[192:195], v203 offset:21504
	ds_read_b128 v[196:199], v203 offset:22528
	ds_read_b128 v[204:207], v203 offset:23552
	global_load_lds_dwordx4 v[208:209], off
	s_add_i32 m0, s44, 0x2000
	s_add_u32 s44, s58, 0x40000
	v_lshl_add_u64 v[210:211], s[58:59], 0, v[146:147]
	s_addc_u32 s45, s59, 0
	s_add_i32 s8, s8, s14
	global_load_lds_dwordx4 v[210:211], off
	v_lshl_add_u64 v[214:215], s[44:45], 0, v[128:129]
	s_mov_b32 m0, s8
	v_lshl_add_u64 v[222:223], s[92:93], 0, v[148:149]
	global_load_lds_dwordx4 v[214:215], off
	v_lshl_add_u64 v[214:215], s[44:45], 0, v[146:147]
	s_add_i32 m0, s8, 0x2000
	s_nop 0
	global_load_lds_dwordx4 v[214:215], off
	v_lshl_add_u64 v[214:215], s[92:93], 0, v[150:151]
	s_mov_b32 m0, s15
	s_nop 0
	global_load_lds_dwordx4 v[214:215], off
	s_mov_b32 m0, s17
	s_nop 0
	global_load_lds_dwordx4 v[222:223], off
	s_nop 0
	s_waitcnt vmcnt(8)
	s_waitcnt lgkmcnt(0)
	s_barrier
; #define PG8_STAGE(bufoff, gbase, voff) do { _Pragma("unroll") for (int _i = 0; _i < 2; ++_i) \
;         __builtin_amdgcn_global_load_lds((const unsigned*)((const char*)(gbase) + (voff)[_i]), (PG8_LAS unsigned*)(lds + (bufoff) + ldsw + _i * 8192), 16, 0, 0); } while (0)
; #define PG8_LDA(dst, b, h) do { _Pragma("unroll") for (int m = 0; m < 4; ++m) _Pragma("unroll") for (int k = 0; k < 2; ++k) dst[m][k] = *(const PG8_LAS bf16x8*)(lds + PG8_SA(b, h) + aoff + m * 2048 + k * 1024); } while (0)
; #define PG8_LDB(dst, b, h) do { _Pragma("unroll") for (int n = 0; n < 2; ++n) _Pragma("unroll") for (int k = 0; k < 2; ++k) dst[n][k] = *(const PG8_LAS bf16x8*)(lds + PG8_SB(b, h) + boff + n * 2048 + k * 1024); } while (0)
; #define PG8_MMA(ai, bj, At, Bt) do { __builtin_amdgcn_s_setprio(1); _Pragma("unroll") for (int m = 0; m < 4; ++m) _Pragma("unroll") for (int n = 0; n < 2; ++n) _Pragma("unroll") for (int k = 0; k < 2; ++k) \
;         acc[ai][bj][m][n] = __builtin_amdgcn_mfma_f32_16x16x32_bf16(Bt[n][k], At[m][k], acc[ai][bj][m][n], 0, 0, 0); __builtin_amdgcn_s_setprio(0); } while (0)
; #define PG8_WAIT_V(n) asm volatile("s_waitcnt vmcnt(" #n ")" ::: "memory")
; #define PG8_WAIT_L(n) asm volatile("s_waitcnt lgkmcnt(" #n ")" ::: "memory")
; #define PG8_BAR __builtin_amdgcn_s_barrier()
; #define PG8_SCHED __builtin_amdgcn_sched_barrier(0)
; template <class Epi, class Sched, bool ALIGN_EPI = false, bool SP2 = false>
; __device__ __forceinline__ void gemm_phase(PG8_LAS unsigned char* lds, const Gemm g, const Sched& S, const Epi& E) {
;     ...
;             PG8_WAIT_V(8); PG8_WAIT_L(0); PG8_BAR; PG8_MMA(1, 0, At, B0); PG8_MMA(1, 1, At, B1); PG8_BAR; PG8_SCHED;
;             PG8_LDB(B0, 1, 0); PG8_LDB(B1, 1, 1); PG8_SCHED; PG8_LDA(At, 1, 0); PG8_STAGE(PG8_SA(0, 1), a2 + hstep, voffA);
;             PG8_WAIT_V(8); PG8_WAIT_L(0); PG8_BAR; PG8_MMA(0, 0, At, B0); PG8_MMA(0, 1, At, B1); PG8_BAR; PG8_SCHED;
	s_waitcnt lgkmcnt(0)
	v_mfma_f32_16x16x32_bf16 v[60:63], v[130:133], v[172:175], v[60:63]
	v_mfma_f32_16x16x32_bf16 v[56:59], v[138:141], v[172:175], v[56:59]
	v_mfma_f32_16x16x32_bf16 v[44:47], v[130:133], v[180:183], v[44:47]
	v_mfma_f32_16x16x32_bf16 v[40:43], v[138:141], v[180:183], v[40:43]
	v_mfma_f32_16x16x32_bf16 v[28:31], v[130:133], v[188:191], v[28:31]
	v_mfma_f32_16x16x32_bf16 v[24:27], v[138:141], v[188:191], v[24:27]
	v_mfma_f32_16x16x32_bf16 v[12:15], v[130:133], v[196:199], v[12:15]
	v_mfma_f32_16x16x32_bf16 v[8:11], v[138:141], v[196:199], v[8:11]
	v_mfma_f32_16x16x32_bf16 v[60:63], v[134:137], v[176:179], v[60:63]
	v_mfma_f32_16x16x32_bf16 v[56:59], v[142:145], v[176:179], v[56:59]
	v_mfma_f32_16x16x32_bf16 v[44:47], v[134:137], v[184:187], v[44:47]
	v_mfma_f32_16x16x32_bf16 v[40:43], v[142:145], v[184:187], v[40:43]
	v_mfma_f32_16x16x32_bf16 v[28:31], v[134:137], v[192:195], v[28:31]
	v_mfma_f32_16x16x32_bf16 v[24:27], v[142:145], v[192:195], v[24:27]
	v_mfma_f32_16x16x32_bf16 v[12:15], v[134:137], v[204:207], v[12:15]
	v_mfma_f32_16x16x32_bf16 v[8:11], v[142:145], v[204:207], v[8:11]
	v_mfma_f32_16x16x32_bf16 v[52:55], v[156:159], v[172:175], v[52:55]
	v_mfma_f32_16x16x32_bf16 v[48:51], v[164:167], v[172:175], v[48:51]
	v_mfma_f32_16x16x32_bf16 v[36:39], v[156:159], v[180:183], v[36:39]
	v_mfma_f32_16x16x32_bf16 v[32:35], v[164:167], v[180:183], v[32:35]
	v_mfma_f32_16x16x32_bf16 v[20:23], v[156:159], v[188:191], v[20:23]
	v_mfma_f32_16x16x32_bf16 v[16:19], v[164:167], v[188:191], v[16:19]
	v_mfma_f32_16x16x32_bf16 v[4:7], v[156:159], v[196:199], v[4:7]
	v_mfma_f32_16x16x32_bf16 v[0:3], v[164:167], v[196:199], v[0:3]
	v_mfma_f32_16x16x32_bf16 v[52:55], v[160:163], v[176:179], v[52:55]
	v_mfma_f32_16x16x32_bf16 v[48:51], v[168:171], v[176:179], v[48:51]
	v_mfma_f32_16x16x32_bf16 v[36:39], v[160:163], v[184:187], v[36:39]
	v_mfma_f32_16x16x32_bf16 v[32:35], v[168:171], v[184:187], v[32:35]
	v_mfma_f32_16x16x32_bf16 v[20:23], v[160:163], v[192:195], v[20:23]
	v_mfma_f32_16x16x32_bf16 v[16:19], v[168:171], v[192:195], v[16:19]
	v_mfma_f32_16x16x32_bf16 v[4:7], v[160:163], v[204:207], v[4:7]
	v_mfma_f32_16x16x32_bf16 v[0:3], v[168:171], v[204:207], v[0:3]
	s_barrier
	s_add_i32 s8, 0, 0x18000
	s_add_i32 s85, 0, 0x1c000
	v_add_u32_e32 v142, s8, v201
	v_add_u32_e32 v168, s85, v201
	ds_read_b128 v[130:133], v142
	ds_read_b128 v[134:137], v142 offset:1024
	ds_read_b128 v[138:141], v142 offset:2048
	ds_read_b128 v[142:145], v142 offset:3072
	ds_read_b128 v[156:159], v168
	ds_read_b128 v[160:163], v168 offset:1024
	ds_read_b128 v[164:167], v168 offset:2048
	ds_read_b128 v[168:171], v168 offset:3072
	s_add_u32 s44, s92, 0x40000
	s_addc_u32 s45, s93, 0
	s_mov_b32 m0, s18
	v_lshl_add_u64 v[228:229], s[44:45], 0, v[150:151]
	ds_read_b128 v[172:175], v203 offset:32768
	ds_read_b128 v[176:179], v203 offset:33792
	ds_read_b128 v[180:183], v203 offset:34816
	ds_read_b128 v[184:187], v203 offset:35840
	ds_read_b128 v[188:191], v203 offset:36864
	ds_read_b128 v[192:195], v203 offset:37888
	ds_read_b128 v[196:199], v203 offset:38912
	ds_read_b128 v[204:207], v203 offset:39936
	global_load_lds_dwordx4 v[228:229], off
	v_lshl_add_u64 v[228:229], s[44:45], 0, v[148:149]
	s_mov_b32 m0, s19
	s_nop 0
	global_load_lds_dwordx4 v[228:229], off
	s_nop 0
	s_waitcnt vmcnt(8)
	s_waitcnt lgkmcnt(0)
	s_barrier
	s_waitcnt lgkmcnt(0)
	v_mfma_f32_16x16x32_bf16 v[124:127], v[130:133], v[172:175], v[124:127]
	v_mfma_f32_16x16x32_bf16 v[120:123], v[138:141], v[172:175], v[120:123]
	v_mfma_f32_16x16x32_bf16 v[108:111], v[130:133], v[180:183], v[108:111]
	v_mfma_f32_16x16x32_bf16 v[104:107], v[138:141], v[180:183], v[104:107]
	v_mfma_f32_16x16x32_bf16 v[92:95], v[130:133], v[188:191], v[92:95]
	v_mfma_f32_16x16x32_bf16 v[88:91], v[138:141], v[188:191], v[88:91]
	v_mfma_f32_16x16x32_bf16 v[76:79], v[130:133], v[196:199], v[76:79]
	v_mfma_f32_16x16x32_bf16 v[72:75], v[138:141], v[196:199], v[72:75]
	v_mfma_f32_16x16x32_bf16 v[124:127], v[134:137], v[176:179], v[124:127]
	v_mfma_f32_16x16x32_bf16 v[120:123], v[142:145], v[176:179], v[120:123]
	v_mfma_f32_16x16x32_bf16 v[108:111], v[134:137], v[184:187], v[108:111]
	v_mfma_f32_16x16x32_bf16 v[104:107], v[142:145], v[184:187], v[104:107]
	v_mfma_f32_16x16x32_bf16 v[92:95], v[134:137], v[192:195], v[92:95]
	v_mfma_f32_16x16x32_bf16 v[88:91], v[142:145], v[192:195], v[88:91]
	v_mfma_f32_16x16x32_bf16 v[76:79], v[134:137], v[204:207], v[76:79]
	v_mfma_f32_16x16x32_bf16 v[72:75], v[142:145], v[204:207], v[72:75]
	v_mfma_f32_16x16x32_bf16 v[116:119], v[156:159], v[172:175], v[116:119]
	v_mfma_f32_16x16x32_bf16 v[112:115], v[164:167], v[172:175], v[112:115]
	v_mfma_f32_16x16x32_bf16 v[100:103], v[156:159], v[180:183], v[100:103]
	v_mfma_f32_16x16x32_bf16 v[96:99], v[164:167], v[180:183], v[96:99]
	v_mfma_f32_16x16x32_bf16 v[84:87], v[156:159], v[188:191], v[84:87]
	v_mfma_f32_16x16x32_bf16 v[80:83], v[164:167], v[188:191], v[80:83]
	v_mfma_f32_16x16x32_bf16 v[68:71], v[156:159], v[196:199], v[68:71]
	v_mfma_f32_16x16x32_bf16 v[64:67], v[164:167], v[196:199], v[64:67]
	v_mfma_f32_16x16x32_bf16 v[116:119], v[160:163], v[176:179], v[116:119]
	v_mfma_f32_16x16x32_bf16 v[112:115], v[168:171], v[176:179], v[112:115]
	v_mfma_f32_16x16x32_bf16 v[100:103], v[160:163], v[184:187], v[100:103]
	v_mfma_f32_16x16x32_bf16 v[96:99], v[168:171], v[184:187], v[96:99]
	v_mfma_f32_16x16x32_bf16 v[84:87], v[160:163], v[192:195], v[84:87]
	v_mfma_f32_16x16x32_bf16 v[80:83], v[168:171], v[192:195], v[80:83]
	v_mfma_f32_16x16x32_bf16 v[68:71], v[160:163], v[204:207], v[68:71]
	v_mfma_f32_16x16x32_bf16 v[64:67], v[168:171], v[204:207], v[64:67]
	s_barrier
; #define PG8_STAGE(bufoff, gbase, voff) do { _Pragma("unroll") for (int _i = 0; _i < 2; ++_i) \
;         __builtin_amdgcn_global_load_lds((const unsigned*)((const char*)(gbase) + (voff)[_i]), (PG8_LAS unsigned*)(lds + (bufoff) + ldsw + _i * 8192), 16, 0, 0); } while (0)
; #define PG8_LDA(dst, b, h) do { _Pragma("unroll") for (int m = 0; m < 4; ++m) _Pragma("unroll") for (int k = 0; k < 2; ++k) dst[m][k] = *(const PG8_LAS bf16x8*)(lds + PG8_SA(b, h) + aoff + m * 2048 + k * 1024); } while (0)
; #define PG8_MMA(ai, bj, At, Bt) do { __builtin_amdgcn_s_setprio(1); _Pragma("unroll") for (int m = 0; m < 4; ++m) _Pragma("unroll") for (int n = 0; n < 2; ++n) _Pragma("unroll") for (int k = 0; k < 2; ++k) \
;         acc[ai][bj][m][n] = __builtin_amdgcn_mfma_f32_16x16x32_bf16(Bt[n][k], At[m][k], acc[ai][bj][m][n], 0, 0, 0); __builtin_amdgcn_s_setprio(0); } while (0)
; #define PG8_WAIT_V(n) asm volatile("s_waitcnt vmcnt(" #n ")" ::: "memory")
; #define PG8_WAIT_L(n) asm volatile("s_waitcnt lgkmcnt(" #n ")" ::: "memory")
; #define PG8_BAR __builtin_amdgcn_s_barrier()
; #define PG8_SCHED __builtin_amdgcn_sched_barrier(0)
; template <class Epi, class Sched, bool ALIGN_EPI = false, bool SP2 = false>
; __device__ __forceinline__ void gemm_phase(PG8_LAS unsigned char* lds, const Gemm g, const Sched& S, const Epi& E) {
;     ...
;             PG8_LDA(At, 1, 1); PG8_STAGE(PG8_SB(1, 0), b3, voffB); PG8_STAGE(PG8_SB(1, 1), b3 + hstep, voffB); PG8_STAGE(PG8_SA(1, 0), a3, voffA);
;             PG8_WAIT_V(8); PG8_WAIT_L(0); PG8_BAR; PG8_MMA(1, 0, At, B0); PG8_MMA(1, 1, At, B1); PG8_BAR; PG8_SCHED;
	s_add_i32 s8, s8, s14
	v_lshl_add_u64 v[208:209], v[208:209], 0, s[90:91]
	s_mov_b32 m0, s8
	ds_read_b128 v[172:175], v203 offset:49152
	ds_read_b128 v[176:179], v203 offset:50176
	ds_read_b128 v[180:183], v203 offset:51200
	ds_read_b128 v[184:187], v203 offset:52224
	ds_read_b128 v[188:191], v203 offset:53248
	ds_read_b128 v[192:195], v203 offset:54272
	ds_read_b128 v[196:199], v203 offset:55296
	ds_read_b128 v[204:207], v203 offset:56320
	global_load_lds_dwordx4 v[208:209], off
	s_add_i32 m0, s8, 0x2000
	s_add_u32 s44, s58, 0x40080
	v_lshl_add_u64 v[208:209], v[210:211], 0, s[90:91]
	s_addc_u32 s45, s59, 0
	s_add_i32 s8, s85, s14
	global_load_lds_dwordx4 v[208:209], off
	v_lshl_add_u64 v[208:209], s[44:45], 0, v[128:129]
	s_mov_b32 m0, s8
	s_nop 0
	global_load_lds_dwordx4 v[208:209], off
	v_lshl_add_u64 v[208:209], s[44:45], 0, v[146:147]
	s_add_i32 m0, s8, 0x2000
	s_nop 0
	global_load_lds_dwordx4 v[208:209], off
	v_lshl_add_u64 v[208:209], v[214:215], 0, s[90:91]
	s_mov_b32 m0, s30
	s_nop 0
	global_load_lds_dwordx4 v[208:209], off
	v_lshl_add_u64 v[208:209], v[222:223], 0, s[90:91]
	s_mov_b32 m0, s31
	s_nop 0
	global_load_lds_dwordx4 v[208:209], off
	s_waitcnt vmcnt(8)
	s_waitcnt lgkmcnt(0)
	s_barrier
	s_waitcnt lgkmcnt(0)
	v_mfma_f32_16x16x32_bf16 v[60:63], v[130:133], v[172:175], v[60:63]
	v_mfma_f32_16x16x32_bf16 v[56:59], v[138:141], v[172:175], v[56:59]
	v_mfma_f32_16x16x32_bf16 v[44:47], v[130:133], v[180:183], v[44:47]
	v_mfma_f32_16x16x32_bf16 v[40:43], v[138:141], v[180:183], v[40:43]
	v_mfma_f32_16x16x32_bf16 v[28:31], v[130:133], v[188:191], v[28:31]
	v_mfma_f32_16x16x32_bf16 v[24:27], v[138:141], v[188:191], v[24:27]
	v_mfma_f32_16x16x32_bf16 v[12:15], v[130:133], v[196:199], v[12:15]
	v_mfma_f32_16x16x32_bf16 v[8:11], v[138:141], v[196:199], v[8:11]
	v_mfma_f32_16x16x32_bf16 v[60:63], v[134:137], v[176:179], v[60:63]
	v_mfma_f32_16x16x32_bf16 v[56:59], v[142:145], v[176:179], v[56:59]
	v_mfma_f32_16x16x32_bf16 v[44:47], v[134:137], v[184:187], v[44:47]
	v_mfma_f32_16x16x32_bf16 v[40:43], v[142:145], v[184:187], v[40:43]
	v_mfma_f32_16x16x32_bf16 v[28:31], v[134:137], v[192:195], v[28:31]
	v_mfma_f32_16x16x32_bf16 v[24:27], v[142:145], v[192:195], v[24:27]
	v_mfma_f32_16x16x32_bf16 v[12:15], v[134:137], v[204:207], v[12:15]
	v_mfma_f32_16x16x32_bf16 v[8:11], v[142:145], v[204:207], v[8:11]
	v_mfma_f32_16x16x32_bf16 v[52:55], v[156:159], v[172:175], v[52:55]
	v_mfma_f32_16x16x32_bf16 v[48:51], v[164:167], v[172:175], v[48:51]
	v_mfma_f32_16x16x32_bf16 v[36:39], v[156:159], v[180:183], v[36:39]
	v_mfma_f32_16x16x32_bf16 v[32:35], v[164:167], v[180:183], v[32:35]
	v_mfma_f32_16x16x32_bf16 v[20:23], v[156:159], v[188:191], v[20:23]
	v_mfma_f32_16x16x32_bf16 v[16:19], v[164:167], v[188:191], v[16:19]
	v_mfma_f32_16x16x32_bf16 v[4:7], v[156:159], v[196:199], v[4:7]
	v_mfma_f32_16x16x32_bf16 v[0:3], v[164:167], v[196:199], v[0:3]
	v_mfma_f32_16x16x32_bf16 v[52:55], v[160:163], v[176:179], v[52:55]
	v_mfma_f32_16x16x32_bf16 v[48:51], v[168:171], v[176:179], v[48:51]
	v_mfma_f32_16x16x32_bf16 v[36:39], v[160:163], v[184:187], v[36:39]
	v_mfma_f32_16x16x32_bf16 v[32:35], v[168:171], v[184:187], v[32:35]
	v_mfma_f32_16x16x32_bf16 v[20:23], v[160:163], v[192:195], v[20:23]
	v_mfma_f32_16x16x32_bf16 v[16:19], v[168:171], v[192:195], v[16:19]
	v_mfma_f32_16x16x32_bf16 v[4:7], v[160:163], v[204:207], v[4:7]
	v_mfma_f32_16x16x32_bf16 v[0:3], v[168:171], v[204:207], v[0:3]
	s_barrier
	s_add_i32 s84, s84, 2
	s_add_u32 vcc_lo, vcc_lo, 0x100
	s_addc_u32 vcc_hi, vcc_hi, 0
	s_add_u32 s88, s88, 0x100
	s_addc_u32 s94, s94, 0
	s_cmp_gt_u32 s84, 13
	s_cbranch_scc0 .LBB0_564
	s_setprio 0
	s_and_b64 vcc, exec, s[62:63]
	s_cbranch_vccz .LBB0_567
	s_barrier

; #define PG8_STAGE(bufoff, gbase, voff) do { _Pragma("unroll") for (int _i = 0; _i < 2; ++_i) \
;         __builtin_amdgcn_global_load_lds((const unsigned*)((const char*)(gbase) + (voff)[_i]), (PG8_LAS unsigned*)(lds + (bufoff) + ldsw + _i * 8192), 16, 0, 0); } while (0)
; #define PG8_LDA(dst, b, h) do { _Pragma("unroll") for (int m = 0; m < 4; ++m) _Pragma("unroll") for (int k = 0; k < 2; ++k) dst[m][k] = *(const PG8_LAS bf16x8*)(lds + PG8_SA(b, h) + aoff + m * 2048 + k * 1024); } while (0)
; #define PG8_LDB(dst, b, h) do { _Pragma("unroll") for (int n = 0; n < 2; ++n) _Pragma("unroll") for (int k = 0; k < 2; ++k) dst[n][k] = *(const PG8_LAS bf16x8*)(lds + PG8_SB(b, h) + boff + n * 2048 + k * 1024); } while (0)
; #define PG8_MMA(ai, bj, At, Bt) do { __builtin_amdgcn_s_setprio(1); _Pragma("unroll") for (int m = 0; m < 4; ++m) _Pragma("unroll") for (int n = 0; n < 2; ++n) _Pragma("unroll") for (int k = 0; k < 2; ++k) \
;         acc[ai][bj][m][n] = __builtin_amdgcn_mfma_f32_16x16x32_bf16(Bt[n][k], At[m][k], acc[ai][bj][m][n], 0, 0, 0); __builtin_amdgcn_s_setprio(0); } while (0)
; #define PG8_WAIT_V(n) asm volatile("s_waitcnt vmcnt(" #n ")" ::: "memory")
; #define PG8_WAIT_L(n) asm volatile("s_waitcnt lgkmcnt(" #n ")" ::: "memory")
; #define PG8_BAR __builtin_amdgcn_s_barrier()
; #define PG8_SCHED __builtin_amdgcn_sched_barrier(0)
; template <class Epi, class Sched, bool ALIGN_EPI = false, bool SP2 = false>
; __device__ __forceinline__ void gemm_phase(PG8_LAS unsigned char* lds, const Gemm g, const Sched& S, const Epi& E) {
;     ...
;             const bool last = (t == nt - 2);
;             const char* a1 = cA + (size_t)(t + 1) * kstep;
;             const char* a2 = last ? nA : cA + (size_t)(t + 2) * kstep; const char* b2 = last ? nB : cB + (size_t)(t + 2) * kstep;
;             const char* a3 = a2 + kstep; const char* b3 = b2 + kstep;
;             if (last && has_next) S.a_ready(nxt);
;             if constexpr (SP2) {
;             PG8_LDB(B0, 0, 0); PG8_LDB(B1, 0, 1); PG8_SCHED; PG8_LDA(At, 0, 0); PG8_STAGE(PG8_SA(1, 1), a1 + hstep, voffA);
;             PG8_WAIT_V(8); PG8_WAIT_L(0); PG8_BAR; PG8_MMA(0, 0, At, B0); PG8_MMA(0, 1, At, B1); PG8_BAR; PG8_SCHED;
;             PG8_LDA(At, 0, 1); PG8_STAGE(PG8_SB(0, 0), b2, voffB); PG8_STAGE(PG8_SB(0, 1), b2 + hstep, voffB); PG8_STAGE(PG8_SA(0, 0), a2, voffA);
.Lsp_3:
.LBB0_598:
	s_add_u32 s58, vcc_lo, 0xfffc0080
	s_addc_u32 s59, vcc_hi, -1
	s_add_i32 s84, 0, 0x10000
	s_cmp_eq_u32 s94, 12
	s_cselect_b32 s65, s35, s59
	s_cselect_b32 s64, s36, s58
	s_cselect_b32 s59, s37, s93
	s_cselect_b32 s58, s43, s88
	s_add_i32 s97, 0, 0x14000
	v_add_u32_e32 v76, s84, v228
	v_add_u32_e32 v168, s97, v228
	ds_read_b128 v[64:67], v76
	ds_read_b128 v[68:71], v76 offset:1024
	ds_read_b128 v[72:75], v76 offset:2048
	ds_read_b128 v[76:79], v76 offset:3072
	ds_read_b128 v[156:159], v168
	ds_read_b128 v[160:163], v168 offset:1024
	ds_read_b128 v[164:167], v168 offset:2048
	ds_read_b128 v[168:171], v168 offset:3072
	v_lshl_add_u64 v[204:205], vcc, 0, v[152:153]
	s_add_i32 m0, s18, 0xc000
	ds_read_b128 v[172:175], v230
	ds_read_b128 v[176:179], v230 offset:1024
	ds_read_b128 v[180:183], v230 offset:2048
	ds_read_b128 v[184:187], v230 offset:3072
	ds_read_b128 v[188:191], v230 offset:4096
	ds_read_b128 v[192:195], v230 offset:5120
	ds_read_b128 v[196:199], v230 offset:6144
	ds_read_b128 v[200:203], v230 offset:7168
	global_load_lds_dwordx4 v[204:205], off
	v_lshl_add_u64 v[204:205], vcc, 0, v[154:155]
	s_add_i32 m0, s18, 0xe000
	s_nop 0
	global_load_lds_dwordx4 v[204:205], off
	s_waitcnt vmcnt(8)
	s_waitcnt lgkmcnt(0)
	s_barrier
	s_waitcnt lgkmcnt(0)
	v_mfma_f32_16x16x32_bf16 v[142:145], v[64:67], v[172:175], v[142:145]
	v_mfma_f32_16x16x32_bf16 v[138:141], v[72:75], v[172:175], v[138:141]
	v_mfma_f32_16x16x32_bf16 v[134:137], v[64:67], v[180:183], v[134:137]
	v_mfma_f32_16x16x32_bf16 v[124:127], v[72:75], v[180:183], v[124:127]
	v_mfma_f32_16x16x32_bf16 v[108:111], v[64:67], v[188:191], v[108:111]
	v_mfma_f32_16x16x32_bf16 v[104:107], v[72:75], v[188:191], v[104:107]
	v_mfma_f32_16x16x32_bf16 v[100:103], v[64:67], v[196:199], v[100:103]
	v_mfma_f32_16x16x32_bf16 v[92:95], v[72:75], v[196:199], v[92:95]
	v_mfma_f32_16x16x32_bf16 v[142:145], v[68:71], v[176:179], v[142:145]
	v_mfma_f32_16x16x32_bf16 v[138:141], v[76:79], v[176:179], v[138:141]
	v_mfma_f32_16x16x32_bf16 v[134:137], v[68:71], v[184:187], v[134:137]
	v_mfma_f32_16x16x32_bf16 v[124:127], v[76:79], v[184:187], v[124:127]
	v_mfma_f32_16x16x32_bf16 v[108:111], v[68:71], v[192:195], v[108:111]
	v_mfma_f32_16x16x32_bf16 v[104:107], v[76:79], v[192:195], v[104:107]
	v_mfma_f32_16x16x32_bf16 v[100:103], v[68:71], v[200:203], v[100:103]
	v_mfma_f32_16x16x32_bf16 v[92:95], v[76:79], v[200:203], v[92:95]
	v_mfma_f32_16x16x32_bf16 v[130:133], v[156:159], v[172:175], v[130:133]
	v_mfma_f32_16x16x32_bf16 v[120:123], v[164:167], v[172:175], v[120:123]
	v_mfma_f32_16x16x32_bf16 v[116:119], v[156:159], v[180:183], v[116:119]
	v_mfma_f32_16x16x32_bf16 v[112:115], v[164:167], v[180:183], v[112:115]
	v_mfma_f32_16x16x32_bf16 v[96:99], v[156:159], v[188:191], v[96:99]
	v_mfma_f32_16x16x32_bf16 v[88:91], v[164:167], v[188:191], v[88:91]
	v_mfma_f32_16x16x32_bf16 v[84:87], v[156:159], v[196:199], v[84:87]
	v_mfma_f32_16x16x32_bf16 v[80:83], v[164:167], v[196:199], v[80:83]
	v_mfma_f32_16x16x32_bf16 v[130:133], v[160:163], v[176:179], v[130:133]
	v_mfma_f32_16x16x32_bf16 v[120:123], v[168:171], v[176:179], v[120:123]
	v_mfma_f32_16x16x32_bf16 v[116:119], v[160:163], v[184:187], v[116:119]
	v_mfma_f32_16x16x32_bf16 v[112:115], v[168:171], v[184:187], v[112:115]
	v_mfma_f32_16x16x32_bf16 v[96:99], v[160:163], v[192:195], v[96:99]
	v_mfma_f32_16x16x32_bf16 v[88:91], v[168:171], v[192:195], v[88:91]
	v_mfma_f32_16x16x32_bf16 v[84:87], v[160:163], v[200:203], v[84:87]
	v_mfma_f32_16x16x32_bf16 v[80:83], v[168:171], v[200:203], v[80:83]
	s_barrier
	s_add_i32 s84, s84, s17
	v_lshl_add_u64 v[204:205], s[58:59], 0, v[128:129]
	s_mov_b32 m0, s84
	ds_read_b128 v[172:175], v230 offset:16384
	ds_read_b128 v[176:179], v230 offset:17408
	ds_read_b128 v[180:183], v230 offset:18432
	ds_read_b128 v[184:187], v230 offset:19456
	ds_read_b128 v[188:191], v230 offset:20480
	ds_read_b128 v[192:195], v230 offset:21504
	ds_read_b128 v[196:199], v230 offset:22528
	ds_read_b128 v[200:203], v230 offset:23552
	global_load_lds_dwordx4 v[204:205], off
	s_add_i32 m0, s84, 0x2000
	s_add_u32 s84, s58, 0x40000
	v_lshl_add_u64 v[206:207], s[58:59], 0, v[146:147]
	s_addc_u32 s85, s59, 0
	s_add_i32 s97, s97, s17
	global_load_lds_dwordx4 v[206:207], off
	v_lshl_add_u64 v[208:209], s[84:85], 0, v[128:129]
	s_mov_b32 m0, s97
	v_lshl_add_u64 v[210:211], s[64:65], 0, v[148:149]
	global_load_lds_dwordx4 v[208:209], off
	v_lshl_add_u64 v[208:209], s[84:85], 0, v[146:147]
	s_add_i32 m0, s97, 0x2000
	s_nop 0
	global_load_lds_dwordx4 v[208:209], off
	v_lshl_add_u64 v[208:209], s[64:65], 0, v[150:151]
	s_mov_b32 m0, s18
	s_nop 0
	global_load_lds_dwordx4 v[208:209], off
	s_mov_b32 m0, s19
	s_nop 0
	global_load_lds_dwordx4 v[210:211], off
	s_nop 0
	s_waitcnt vmcnt(8)
	s_waitcnt lgkmcnt(0)
	s_barrier
; #define PG8_STAGE(bufoff, gbase, voff) do { _Pragma("unroll") for (int _i = 0; _i < 2; ++_i) \
;         __builtin_amdgcn_global_load_lds((const unsigned*)((const char*)(gbase) + (voff)[_i]), (PG8_LAS unsigned*)(lds + (bufoff) + ldsw + _i * 8192), 16, 0, 0); } while (0)
; #define PG8_LDA(dst, b, h) do { _Pragma("unroll") for (int m = 0; m < 4; ++m) _Pragma("unroll") for (int k = 0; k < 2; ++k) dst[m][k] = *(const PG8_LAS bf16x8*)(lds + PG8_SA(b, h) + aoff + m * 2048 + k * 1024); } while (0)
; #define PG8_LDB(dst, b, h) do { _Pragma("unroll") for (int n = 0; n < 2; ++n) _Pragma("unroll") for (int k = 0; k < 2; ++k) dst[n][k] = *(const PG8_LAS bf16x8*)(lds + PG8_SB(b, h) + boff + n * 2048 + k * 1024); } while (0)
; #define PG8_MMA(ai, bj, At, Bt) do { __builtin_amdgcn_s_setprio(1); _Pragma("unroll") for (int m = 0; m < 4; ++m) _Pragma("unroll") for (int n = 0; n < 2; ++n) _Pragma("unroll") for (int k = 0; k < 2; ++k) \
;         acc[ai][bj][m][n] = __builtin_amdgcn_mfma_f32_16x16x32_bf16(Bt[n][k], At[m][k], acc[ai][bj][m][n], 0, 0, 0); __builtin_amdgcn_s_setprio(0); } while (0)
; #define PG8_WAIT_V(n) asm volatile("s_waitcnt vmcnt(" #n ")" ::: "memory")
; #define PG8_WAIT_L(n) asm volatile("s_waitcnt lgkmcnt(" #n ")" ::: "memory")
; #define PG8_BAR __builtin_amdgcn_s_barrier()
; #define PG8_SCHED __builtin_amdgcn_sched_barrier(0)
; template <class Epi, class Sched, bool ALIGN_EPI = false, bool SP2 = false>
; __device__ __forceinline__ void gemm_phase(PG8_LAS unsigned char* lds, const Gemm g, const Sched& S, const Epi& E) {
;     ...
;             PG8_WAIT_V(8); PG8_WAIT_L(0); PG8_BAR; PG8_MMA(1, 0, At, B0); PG8_MMA(1, 1, At, B1); PG8_BAR; PG8_SCHED;
;             PG8_LDB(B0, 1, 0); PG8_LDB(B1, 1, 1); PG8_SCHED; PG8_LDA(At, 1, 0); PG8_STAGE(PG8_SA(0, 1), a2 + hstep, voffA);
;             PG8_WAIT_V(8); PG8_WAIT_L(0); PG8_BAR; PG8_MMA(0, 0, At, B0); PG8_MMA(0, 1, At, B1); PG8_BAR; PG8_SCHED;
	s_waitcnt lgkmcnt(0)
	v_mfma_f32_16x16x32_bf16 v[60:63], v[64:67], v[172:175], v[60:63]
	v_mfma_f32_16x16x32_bf16 v[56:59], v[72:75], v[172:175], v[56:59]
	v_mfma_f32_16x16x32_bf16 v[52:55], v[64:67], v[180:183], v[52:55]
	v_mfma_f32_16x16x32_bf16 v[44:47], v[72:75], v[180:183], v[44:47]
	v_mfma_f32_16x16x32_bf16 v[28:31], v[64:67], v[188:191], v[28:31]
	v_mfma_f32_16x16x32_bf16 v[24:27], v[72:75], v[188:191], v[24:27]
	v_mfma_f32_16x16x32_bf16 v[12:15], v[64:67], v[196:199], v[12:15]
	v_mfma_f32_16x16x32_bf16 v[8:11], v[72:75], v[196:199], v[8:11]
	v_mfma_f32_16x16x32_bf16 v[60:63], v[68:71], v[176:179], v[60:63]
	v_mfma_f32_16x16x32_bf16 v[56:59], v[76:79], v[176:179], v[56:59]
	v_mfma_f32_16x16x32_bf16 v[52:55], v[68:71], v[184:187], v[52:55]
	v_mfma_f32_16x16x32_bf16 v[44:47], v[76:79], v[184:187], v[44:47]
	v_mfma_f32_16x16x32_bf16 v[28:31], v[68:71], v[192:195], v[28:31]
	v_mfma_f32_16x16x32_bf16 v[24:27], v[76:79], v[192:195], v[24:27]
	v_mfma_f32_16x16x32_bf16 v[12:15], v[68:71], v[200:203], v[12:15]
	v_mfma_f32_16x16x32_bf16 v[8:11], v[76:79], v[200:203], v[8:11]
	v_mfma_f32_16x16x32_bf16 v[48:51], v[156:159], v[172:175], v[48:51]
	v_mfma_f32_16x16x32_bf16 v[40:43], v[164:167], v[172:175], v[40:43]
	v_mfma_f32_16x16x32_bf16 v[36:39], v[156:159], v[180:183], v[36:39]
	v_mfma_f32_16x16x32_bf16 v[32:35], v[164:167], v[180:183], v[32:35]
	v_mfma_f32_16x16x32_bf16 v[20:23], v[156:159], v[188:191], v[20:23]
	v_mfma_f32_16x16x32_bf16 v[16:19], v[164:167], v[188:191], v[16:19]
	v_mfma_f32_16x16x32_bf16 v[4:7], v[156:159], v[196:199], v[4:7]
	v_mfma_f32_16x16x32_bf16 v[0:3], v[164:167], v[196:199], v[0:3]
	v_mfma_f32_16x16x32_bf16 v[48:51], v[160:163], v[176:179], v[48:51]
	v_mfma_f32_16x16x32_bf16 v[40:43], v[168:171], v[176:179], v[40:43]
	v_mfma_f32_16x16x32_bf16 v[36:39], v[160:163], v[184:187], v[36:39]
	v_mfma_f32_16x16x32_bf16 v[32:35], v[168:171], v[184:187], v[32:35]
	v_mfma_f32_16x16x32_bf16 v[20:23], v[160:163], v[192:195], v[20:23]
	v_mfma_f32_16x16x32_bf16 v[16:19], v[168:171], v[192:195], v[16:19]
	v_mfma_f32_16x16x32_bf16 v[4:7], v[160:163], v[200:203], v[4:7]
	v_mfma_f32_16x16x32_bf16 v[0:3], v[168:171], v[200:203], v[0:3]
	s_barrier
	s_add_i32 s84, 0, 0x18000
	s_add_i32 s85, 0, 0x1c000
	v_add_u32_e32 v76, s84, v228
	v_add_u32_e32 v168, s85, v228
	ds_read_b128 v[64:67], v76
	ds_read_b128 v[68:71], v76 offset:1024
	ds_read_b128 v[72:75], v76 offset:2048
	ds_read_b128 v[76:79], v76 offset:3072
	ds_read_b128 v[156:159], v168
	ds_read_b128 v[160:163], v168 offset:1024
	ds_read_b128 v[164:167], v168 offset:2048
	ds_read_b128 v[168:171], v168 offset:3072
	s_add_u32 s64, s64, 0x40000
	s_addc_u32 s65, s65, 0
	s_mov_b32 m0, s20
	v_lshl_add_u64 v[214:215], s[64:65], 0, v[150:151]
	ds_read_b128 v[172:175], v230 offset:32768
	ds_read_b128 v[176:179], v230 offset:33792
	ds_read_b128 v[180:183], v230 offset:34816
	ds_read_b128 v[184:187], v230 offset:35840
	ds_read_b128 v[188:191], v230 offset:36864
	ds_read_b128 v[192:195], v230 offset:37888
	ds_read_b128 v[196:199], v230 offset:38912
	ds_read_b128 v[200:203], v230 offset:39936
	global_load_lds_dwordx4 v[214:215], off
	v_lshl_add_u64 v[214:215], s[64:65], 0, v[148:149]
	s_mov_b32 m0, s21
	s_nop 0
	global_load_lds_dwordx4 v[214:215], off
	s_nop 0
	s_waitcnt vmcnt(8)
	s_waitcnt lgkmcnt(0)
	s_barrier
	s_waitcnt lgkmcnt(0)
	v_mfma_f32_16x16x32_bf16 v[142:145], v[64:67], v[172:175], v[142:145]
	v_mfma_f32_16x16x32_bf16 v[138:141], v[72:75], v[172:175], v[138:141]
	v_mfma_f32_16x16x32_bf16 v[134:137], v[64:67], v[180:183], v[134:137]
	v_mfma_f32_16x16x32_bf16 v[124:127], v[72:75], v[180:183], v[124:127]
	v_mfma_f32_16x16x32_bf16 v[108:111], v[64:67], v[188:191], v[108:111]
	v_mfma_f32_16x16x32_bf16 v[104:107], v[72:75], v[188:191], v[104:107]
	v_mfma_f32_16x16x32_bf16 v[100:103], v[64:67], v[196:199], v[100:103]
	v_mfma_f32_16x16x32_bf16 v[92:95], v[72:75], v[196:199], v[92:95]
	v_mfma_f32_16x16x32_bf16 v[142:145], v[68:71], v[176:179], v[142:145]
	v_mfma_f32_16x16x32_bf16 v[138:141], v[76:79], v[176:179], v[138:141]
	v_mfma_f32_16x16x32_bf16 v[134:137], v[68:71], v[184:187], v[134:137]
	v_mfma_f32_16x16x32_bf16 v[124:127], v[76:79], v[184:187], v[124:127]
	v_mfma_f32_16x16x32_bf16 v[108:111], v[68:71], v[192:195], v[108:111]
	v_mfma_f32_16x16x32_bf16 v[104:107], v[76:79], v[192:195], v[104:107]
	v_mfma_f32_16x16x32_bf16 v[100:103], v[68:71], v[200:203], v[100:103]
	v_mfma_f32_16x16x32_bf16 v[92:95], v[76:79], v[200:203], v[92:95]
	v_mfma_f32_16x16x32_bf16 v[130:133], v[156:159], v[172:175], v[130:133]
	v_mfma_f32_16x16x32_bf16 v[120:123], v[164:167], v[172:175], v[120:123]
	v_mfma_f32_16x16x32_bf16 v[116:119], v[156:159], v[180:183], v[116:119]
	v_mfma_f32_16x16x32_bf16 v[112:115], v[164:167], v[180:183], v[112:115]
	v_mfma_f32_16x16x32_bf16 v[96:99], v[156:159], v[188:191], v[96:99]
	v_mfma_f32_16x16x32_bf16 v[88:91], v[164:167], v[188:191], v[88:91]
	v_mfma_f32_16x16x32_bf16 v[84:87], v[156:159], v[196:199], v[84:87]
	v_mfma_f32_16x16x32_bf16 v[80:83], v[164:167], v[196:199], v[80:83]
	v_mfma_f32_16x16x32_bf16 v[130:133], v[160:163], v[176:179], v[130:133]
	v_mfma_f32_16x16x32_bf16 v[120:123], v[168:171], v[176:179], v[120:123]
	v_mfma_f32_16x16x32_bf16 v[116:119], v[160:163], v[184:187], v[116:119]
	v_mfma_f32_16x16x32_bf16 v[112:115], v[168:171], v[184:187], v[112:115]
	v_mfma_f32_16x16x32_bf16 v[96:99], v[160:163], v[192:195], v[96:99]
	v_mfma_f32_16x16x32_bf16 v[88:91], v[168:171], v[192:195], v[88:91]
	v_mfma_f32_16x16x32_bf16 v[84:87], v[160:163], v[200:203], v[84:87]
	v_mfma_f32_16x16x32_bf16 v[80:83], v[168:171], v[200:203], v[80:83]
	s_barrier
; #define PG8_STAGE(bufoff, gbase, voff) do { _Pragma("unroll") for (int _i = 0; _i < 2; ++_i) \
;         __builtin_amdgcn_global_load_lds((const unsigned*)((const char*)(gbase) + (voff)[_i]), (PG8_LAS unsigned*)(lds + (bufoff) + ldsw + _i * 8192), 16, 0, 0); } while (0)
; #define PG8_LDA(dst, b, h) do { _Pragma("unroll") for (int m = 0; m < 4; ++m) _Pragma("unroll") for (int k = 0; k < 2; ++k) dst[m][k] = *(const PG8_LAS bf16x8*)(lds + PG8_SA(b, h) + aoff + m * 2048 + k * 1024); } while (0)
; #define PG8_MMA(ai, bj, At, Bt) do { __builtin_amdgcn_s_setprio(1); _Pragma("unroll") for (int m = 0; m < 4; ++m) _Pragma("unroll") for (int n = 0; n < 2; ++n) _Pragma("unroll") for (int k = 0; k < 2; ++k) \
;         acc[ai][bj][m][n] = __builtin_amdgcn_mfma_f32_16x16x32_bf16(Bt[n][k], At[m][k], acc[ai][bj][m][n], 0, 0, 0); __builtin_amdgcn_s_setprio(0); } while (0)
; #define PG8_WAIT_V(n) asm volatile("s_waitcnt vmcnt(" #n ")" ::: "memory")
; #define PG8_WAIT_L(n) asm volatile("s_waitcnt lgkmcnt(" #n ")" ::: "memory")
; #define PG8_BAR __builtin_amdgcn_s_barrier()
; #define PG8_SCHED __builtin_amdgcn_sched_barrier(0)
; template <class Epi, class Sched, bool ALIGN_EPI = false, bool SP2 = false>
; __device__ __forceinline__ void gemm_phase(PG8_LAS unsigned char* lds, const Gemm g, const Sched& S, const Epi& E) {
;     ...
;             PG8_LDA(At, 1, 1); PG8_STAGE(PG8_SB(1, 0), b3, voffB); PG8_STAGE(PG8_SB(1, 1), b3 + hstep, voffB); PG8_STAGE(PG8_SA(1, 0), a3, voffA);
;             PG8_WAIT_V(8); PG8_WAIT_L(0); PG8_BAR; PG8_MMA(1, 0, At, B0); PG8_MMA(1, 1, At, B1); PG8_BAR; PG8_SCHED;
	s_add_i32 s64, s84, s17
	v_lshl_add_u64 v[204:205], v[204:205], 0, s[90:91]
	s_mov_b32 m0, s64
	ds_read_b128 v[172:175], v230 offset:49152
	ds_read_b128 v[176:179], v230 offset:50176
	ds_read_b128 v[180:183], v230 offset:51200
	ds_read_b128 v[184:187], v230 offset:52224
	ds_read_b128 v[188:191], v230 offset:53248
	ds_read_b128 v[192:195], v230 offset:54272
	ds_read_b128 v[196:199], v230 offset:55296
	ds_read_b128 v[200:203], v230 offset:56320
	global_load_lds_dwordx4 v[204:205], off
	s_add_i32 m0, s64, 0x2000
	s_add_u32 s58, s58, 0x40080
	v_lshl_add_u64 v[204:205], v[206:207], 0, s[90:91]
	s_addc_u32 s59, s59, 0
	s_add_i32 s64, s85, s17
	global_load_lds_dwordx4 v[204:205], off
	v_lshl_add_u64 v[204:205], s[58:59], 0, v[128:129]
	s_mov_b32 m0, s64
	s_nop 0
	global_load_lds_dwordx4 v[204:205], off
	v_lshl_add_u64 v[204:205], s[58:59], 0, v[146:147]
	s_add_i32 m0, s64, 0x2000
	s_nop 0
	global_load_lds_dwordx4 v[204:205], off
	v_lshl_add_u64 v[204:205], v[208:209], 0, s[90:91]
	s_mov_b32 m0, s28
	s_nop 0
	global_load_lds_dwordx4 v[204:205], off
	v_lshl_add_u64 v[204:205], v[210:211], 0, s[90:91]
	s_mov_b32 m0, s29
	s_nop 0
	global_load_lds_dwordx4 v[204:205], off
	s_waitcnt vmcnt(8)
	s_waitcnt lgkmcnt(0)
	s_barrier
	s_waitcnt lgkmcnt(0)
	v_mfma_f32_16x16x32_bf16 v[60:63], v[64:67], v[172:175], v[60:63]
	v_mfma_f32_16x16x32_bf16 v[56:59], v[72:75], v[172:175], v[56:59]
	v_mfma_f32_16x16x32_bf16 v[52:55], v[64:67], v[180:183], v[52:55]
	v_mfma_f32_16x16x32_bf16 v[44:47], v[72:75], v[180:183], v[44:47]
	v_mfma_f32_16x16x32_bf16 v[28:31], v[64:67], v[188:191], v[28:31]
	v_mfma_f32_16x16x32_bf16 v[24:27], v[72:75], v[188:191], v[24:27]
	v_mfma_f32_16x16x32_bf16 v[12:15], v[64:67], v[196:199], v[12:15]
	v_mfma_f32_16x16x32_bf16 v[8:11], v[72:75], v[196:199], v[8:11]
	v_mfma_f32_16x16x32_bf16 v[60:63], v[68:71], v[176:179], v[60:63]
	v_mfma_f32_16x16x32_bf16 v[56:59], v[76:79], v[176:179], v[56:59]
	v_mfma_f32_16x16x32_bf16 v[52:55], v[68:71], v[184:187], v[52:55]
	v_mfma_f32_16x16x32_bf16 v[44:47], v[76:79], v[184:187], v[44:47]
	v_mfma_f32_16x16x32_bf16 v[28:31], v[68:71], v[192:195], v[28:31]
	v_mfma_f32_16x16x32_bf16 v[24:27], v[76:79], v[192:195], v[24:27]
	v_mfma_f32_16x16x32_bf16 v[12:15], v[68:71], v[200:203], v[12:15]
	v_mfma_f32_16x16x32_bf16 v[8:11], v[76:79], v[200:203], v[8:11]
	v_mfma_f32_16x16x32_bf16 v[48:51], v[156:159], v[172:175], v[48:51]
	v_mfma_f32_16x16x32_bf16 v[40:43], v[164:167], v[172:175], v[40:43]
	v_mfma_f32_16x16x32_bf16 v[36:39], v[156:159], v[180:183], v[36:39]
	v_mfma_f32_16x16x32_bf16 v[32:35], v[164:167], v[180:183], v[32:35]
	v_mfma_f32_16x16x32_bf16 v[20:23], v[156:159], v[188:191], v[20:23]
	v_mfma_f32_16x16x32_bf16 v[16:19], v[164:167], v[188:191], v[16:19]
	v_mfma_f32_16x16x32_bf16 v[4:7], v[156:159], v[196:199], v[4:7]
	v_mfma_f32_16x16x32_bf16 v[0:3], v[164:167], v[196:199], v[0:3]
	v_mfma_f32_16x16x32_bf16 v[48:51], v[160:163], v[176:179], v[48:51]
	v_mfma_f32_16x16x32_bf16 v[40:43], v[168:171], v[176:179], v[40:43]
	v_mfma_f32_16x16x32_bf16 v[36:39], v[160:163], v[184:187], v[36:39]
	v_mfma_f32_16x16x32_bf16 v[32:35], v[168:171], v[184:187], v[32:35]
	v_mfma_f32_16x16x32_bf16 v[20:23], v[160:163], v[192:195], v[20:23]
	v_mfma_f32_16x16x32_bf16 v[16:19], v[168:171], v[192:195], v[16:19]
	v_mfma_f32_16x16x32_bf16 v[4:7], v[160:163], v[200:203], v[4:7]
	v_mfma_f32_16x16x32_bf16 v[0:3], v[168:171], v[200:203], v[0:3]
	s_barrier
	s_add_i32 s94, s94, 2
	s_add_u32 vcc_lo, vcc_lo, 0x100
	s_addc_u32 vcc_hi, vcc_hi, 0
	s_add_u32 s88, s88, 0x100
	s_addc_u32 s93, s93, 0
	s_cmp_gt_u32 s94, 13
	s_cbranch_scc0 .LBB0_598
	s_setprio 0
	s_and_b64 vcc, exec, s[72:73]
	s_cbranch_vccz .LBB0_601
	s_barrier

; #define PG8_STAGE(bufoff, gbase, voff) do { _Pragma("unroll") for (int _i = 0; _i < 2; ++_i) \
;         __builtin_amdgcn_global_load_lds((const unsigned*)((const char*)(gbase) + (voff)[_i]), (PG8_LAS unsigned*)(lds + (bufoff) + ldsw + _i * 8192), 16, 0, 0); } while (0)
; #define PG8_LDA(dst, b, h) do { _Pragma("unroll") for (int m = 0; m < 4; ++m) _Pragma("unroll") for (int k = 0; k < 2; ++k) dst[m][k] = *(const PG8_LAS bf16x8*)(lds + PG8_SA(b, h) + aoff + m * 2048 + k * 1024); } while (0)
; #define PG8_LDB(dst, b, h) do { _Pragma("unroll") for (int n = 0; n < 2; ++n) _Pragma("unroll") for (int k = 0; k < 2; ++k) dst[n][k] = *(const PG8_LAS bf16x8*)(lds + PG8_SB(b, h) + boff + n * 2048 + k * 1024); } while (0)
; #define PG8_MMA(ai, bj, At, Bt) do { __builtin_amdgcn_s_setprio(1); _Pragma("unroll") for (int m = 0; m < 4; ++m) _Pragma("unroll") for (int n = 0; n < 2; ++n) _Pragma("unroll") for (int k = 0; k < 2; ++k) \
;         acc[ai][bj][m][n] = __builtin_amdgcn_mfma_f32_16x16x32_bf16(Bt[n][k], At[m][k], acc[ai][bj][m][n], 0, 0, 0); __builtin_amdgcn_s_setprio(0); } while (0)
; #define PG8_WAIT_V(n) asm volatile("s_waitcnt vmcnt(" #n ")" ::: "memory")
; #define PG8_WAIT_L(n) asm volatile("s_waitcnt lgkmcnt(" #n ")" ::: "memory")
; #define PG8_BAR __builtin_amdgcn_s_barrier()
; #define PG8_SCHED __builtin_amdgcn_sched_barrier(0)
; template <class Epi, class Sched, bool ALIGN_EPI = false, bool SP2 = false>
; __device__ __forceinline__ void gemm_phase(PG8_LAS unsigned char* lds, const Gemm g, const Sched& S, const Epi& E) {
;     ...
;             const bool last = (t == nt - 2);
;             const char* a1 = cA + (size_t)(t + 1) * kstep;
;             const char* a2 = last ? nA : cA + (size_t)(t + 2) * kstep; const char* b2 = last ? nB : cB + (size_t)(t + 2) * kstep;
;             const char* a3 = a2 + kstep; const char* b3 = b2 + kstep;
;             if (last && has_next) S.a_ready(nxt);
;             if constexpr (SP2) {
;             PG8_LDB(B0, 0, 0); PG8_LDB(B1, 0, 1); PG8_SCHED; PG8_LDA(At, 0, 0); PG8_STAGE(PG8_SA(1, 1), a1 + hstep, voffA);
;             PG8_WAIT_V(8); PG8_WAIT_L(0); PG8_BAR; PG8_MMA(0, 0, At, B0); PG8_MMA(0, 1, At, B1); PG8_BAR; PG8_SCHED;
;             PG8_LDA(At, 0, 1); PG8_STAGE(PG8_SB(0, 0), b2, voffB); PG8_STAGE(PG8_SB(0, 1), b2 + hstep, voffB); PG8_STAGE(PG8_SA(0, 0), a2, voffA);
.Lsp_0:
.LBB0_813:
	s_add_u32 s8, s66, 0xfffc0080
	s_addc_u32 s37, s67, -1
	s_add_i32 s49, 0, 0x10000
	s_cmp_eq_u32 s36, 12
	s_cselect_b32 s65, s28, s37
	s_cselect_b32 s64, s29, s8
	s_cselect_b32 s59, s30, s35
	s_cselect_b32 s58, s31, s34
	s_add_i32 s8, 0, 0x14000
	v_add_u32_e32 v156, s49, v145
	v_add_u32_e32 v172, s8, v145
	ds_read_b128 v[140:143], v156
	ds_read_b128 v[148:151], v156 offset:1024
	ds_read_b128 v[152:155], v156 offset:2048
	ds_read_b128 v[156:159], v156 offset:3072
	ds_read_b128 v[160:163], v172
	ds_read_b128 v[164:167], v172 offset:1024
	ds_read_b128 v[168:171], v172 offset:2048
	ds_read_b128 v[172:175], v172 offset:3072
	v_lshl_add_u64 v[208:209], s[66:67], 0, v[136:137]
	s_add_i32 m0, s18, 0xc000
	ds_read_b128 v[176:179], v147
	ds_read_b128 v[180:183], v147 offset:1024
	ds_read_b128 v[184:187], v147 offset:2048
	ds_read_b128 v[188:191], v147 offset:3072
	ds_read_b128 v[192:195], v147 offset:4096
	ds_read_b128 v[196:199], v147 offset:5120
	ds_read_b128 v[200:203], v147 offset:6144
	ds_read_b128 v[204:207], v147 offset:7168
	global_load_lds_dwordx4 v[208:209], off
	v_lshl_add_u64 v[208:209], s[66:67], 0, v[138:139]
	s_add_i32 m0, s18, 0xe000
	s_nop 0
	global_load_lds_dwordx4 v[208:209], off
	s_nop 0
	s_waitcnt vmcnt(8)
	s_waitcnt lgkmcnt(0)
	s_barrier
	s_waitcnt lgkmcnt(0)
	v_mfma_f32_16x16x32_bf16 v[124:127], v[140:143], v[176:179], v[124:127]
	v_mfma_f32_16x16x32_bf16 v[116:119], v[152:155], v[176:179], v[116:119]
	v_mfma_f32_16x16x32_bf16 v[108:111], v[140:143], v[184:187], v[108:111]
	v_mfma_f32_16x16x32_bf16 v[100:103], v[152:155], v[184:187], v[100:103]
	v_mfma_f32_16x16x32_bf16 v[92:95], v[140:143], v[192:195], v[92:95]
	v_mfma_f32_16x16x32_bf16 v[84:87], v[152:155], v[192:195], v[84:87]
	v_mfma_f32_16x16x32_bf16 v[76:79], v[140:143], v[200:203], v[76:79]
	v_mfma_f32_16x16x32_bf16 v[68:71], v[152:155], v[200:203], v[68:71]
	v_mfma_f32_16x16x32_bf16 v[124:127], v[148:151], v[180:183], v[124:127]
	v_mfma_f32_16x16x32_bf16 v[116:119], v[156:159], v[180:183], v[116:119]
	v_mfma_f32_16x16x32_bf16 v[108:111], v[148:151], v[188:191], v[108:111]
	v_mfma_f32_16x16x32_bf16 v[100:103], v[156:159], v[188:191], v[100:103]
	v_mfma_f32_16x16x32_bf16 v[92:95], v[148:151], v[196:199], v[92:95]
	v_mfma_f32_16x16x32_bf16 v[84:87], v[156:159], v[196:199], v[84:87]
	v_mfma_f32_16x16x32_bf16 v[76:79], v[148:151], v[204:207], v[76:79]
	v_mfma_f32_16x16x32_bf16 v[68:71], v[156:159], v[204:207], v[68:71]
	v_mfma_f32_16x16x32_bf16 v[120:123], v[160:163], v[176:179], v[120:123]
	v_mfma_f32_16x16x32_bf16 v[112:115], v[168:171], v[176:179], v[112:115]
	v_mfma_f32_16x16x32_bf16 v[104:107], v[160:163], v[184:187], v[104:107]
	v_mfma_f32_16x16x32_bf16 v[96:99], v[168:171], v[184:187], v[96:99]
	v_mfma_f32_16x16x32_bf16 v[88:91], v[160:163], v[192:195], v[88:91]
	v_mfma_f32_16x16x32_bf16 v[80:83], v[168:171], v[192:195], v[80:83]
	v_mfma_f32_16x16x32_bf16 v[72:75], v[160:163], v[200:203], v[72:75]
	v_mfma_f32_16x16x32_bf16 v[64:67], v[168:171], v[200:203], v[64:67]
	v_mfma_f32_16x16x32_bf16 v[120:123], v[164:167], v[180:183], v[120:123]
	v_mfma_f32_16x16x32_bf16 v[112:115], v[172:175], v[180:183], v[112:115]
	v_mfma_f32_16x16x32_bf16 v[104:107], v[164:167], v[188:191], v[104:107]
	v_mfma_f32_16x16x32_bf16 v[96:99], v[172:175], v[188:191], v[96:99]
	v_mfma_f32_16x16x32_bf16 v[88:91], v[164:167], v[196:199], v[88:91]
	v_mfma_f32_16x16x32_bf16 v[80:83], v[172:175], v[196:199], v[80:83]
	v_mfma_f32_16x16x32_bf16 v[72:75], v[164:167], v[204:207], v[72:75]
	v_mfma_f32_16x16x32_bf16 v[64:67], v[172:175], v[204:207], v[64:67]
	s_barrier
	s_add_i32 s37, s49, s17
	v_lshl_add_u64 v[208:209], s[58:59], 0, v[128:129]
	s_mov_b32 m0, s37
	ds_read_b128 v[176:179], v147 offset:16384
	ds_read_b128 v[180:183], v147 offset:17408
	ds_read_b128 v[184:187], v147 offset:18432
	ds_read_b128 v[188:191], v147 offset:19456
	ds_read_b128 v[192:195], v147 offset:20480
	ds_read_b128 v[196:199], v147 offset:21504
	ds_read_b128 v[200:203], v147 offset:22528
	ds_read_b128 v[204:207], v147 offset:23552
	global_load_lds_dwordx4 v[208:209], off
	s_add_i32 m0, s37, 0x2000
	s_add_u32 s72, s58, 0x40000
	v_lshl_add_u64 v[210:211], s[58:59], 0, v[130:131]
	s_addc_u32 s73, s59, 0
	s_add_i32 s8, s8, s17
	global_load_lds_dwordx4 v[210:211], off
	v_lshl_add_u64 v[214:215], s[72:73], 0, v[128:129]
	s_mov_b32 m0, s8
	v_lshl_add_u64 v[222:223], s[64:65], 0, v[132:133]
	global_load_lds_dwordx4 v[214:215], off
	v_lshl_add_u64 v[214:215], s[72:73], 0, v[130:131]
	s_add_i32 m0, s8, 0x2000
	s_nop 0
	global_load_lds_dwordx4 v[214:215], off
	v_lshl_add_u64 v[214:215], s[64:65], 0, v[134:135]
	s_mov_b32 m0, s18
	s_nop 0
	global_load_lds_dwordx4 v[214:215], off
	s_mov_b32 m0, s19
	s_nop 0
	global_load_lds_dwordx4 v[222:223], off
	s_nop 0
	s_waitcnt vmcnt(8)
	s_waitcnt lgkmcnt(0)
	s_barrier
; #define PG8_STAGE(bufoff, gbase, voff) do { _Pragma("unroll") for (int _i = 0; _i < 2; ++_i) \
;         __builtin_amdgcn_global_load_lds((const unsigned*)((const char*)(gbase) + (voff)[_i]), (PG8_LAS unsigned*)(lds + (bufoff) + ldsw + _i * 8192), 16, 0, 0); } while (0)
; #define PG8_LDA(dst, b, h) do { _Pragma("unroll") for (int m = 0; m < 4; ++m) _Pragma("unroll") for (int k = 0; k < 2; ++k) dst[m][k] = *(const PG8_LAS bf16x8*)(lds + PG8_SA(b, h) + aoff + m * 2048 + k * 1024); } while (0)
; #define PG8_LDB(dst, b, h) do { _Pragma("unroll") for (int n = 0; n < 2; ++n) _Pragma("unroll") for (int k = 0; k < 2; ++k) dst[n][k] = *(const PG8_LAS bf16x8*)(lds + PG8_SB(b, h) + boff + n * 2048 + k * 1024); } while (0)
; #define PG8_MMA(ai, bj, At, Bt) do { __builtin_amdgcn_s_setprio(1); _Pragma("unroll") for (int m = 0; m < 4; ++m) _Pragma("unroll") for (int n = 0; n < 2; ++n) _Pragma("unroll") for (int k = 0; k < 2; ++k) \
;         acc[ai][bj][m][n] = __builtin_amdgcn_mfma_f32_16x16x32_bf16(Bt[n][k], At[m][k], acc[ai][bj][m][n], 0, 0, 0); __builtin_amdgcn_s_setprio(0); } while (0)
; #define PG8_WAIT_V(n) asm volatile("s_waitcnt vmcnt(" #n ")" ::: "memory")
; #define PG8_WAIT_L(n) asm volatile("s_waitcnt lgkmcnt(" #n ")" ::: "memory")
; #define PG8_BAR __builtin_amdgcn_s_barrier()
; #define PG8_SCHED __builtin_amdgcn_sched_barrier(0)
; template <class Epi, class Sched, bool ALIGN_EPI = false, bool SP2 = false>
; __device__ __forceinline__ void gemm_phase(PG8_LAS unsigned char* lds, const Gemm g, const Sched& S, const Epi& E) {
;     ...
;             PG8_WAIT_V(8); PG8_WAIT_L(0); PG8_BAR; PG8_MMA(1, 0, At, B0); PG8_MMA(1, 1, At, B1); PG8_BAR; PG8_SCHED;
;             PG8_LDB(B0, 1, 0); PG8_LDB(B1, 1, 1); PG8_SCHED; PG8_LDA(At, 1, 0); PG8_STAGE(PG8_SA(0, 1), a2 + hstep, voffA);
;             PG8_WAIT_V(8); PG8_WAIT_L(0); PG8_BAR; PG8_MMA(0, 0, At, B0); PG8_MMA(0, 1, At, B1); PG8_BAR; PG8_SCHED;
	s_waitcnt lgkmcnt(0)
	v_mfma_f32_16x16x32_bf16 v[60:63], v[140:143], v[176:179], v[60:63]
	v_mfma_f32_16x16x32_bf16 v[52:55], v[152:155], v[176:179], v[52:55]
	v_mfma_f32_16x16x32_bf16 v[44:47], v[140:143], v[184:187], v[44:47]
	v_mfma_f32_16x16x32_bf16 v[36:39], v[152:155], v[184:187], v[36:39]
	v_mfma_f32_16x16x32_bf16 v[28:31], v[140:143], v[192:195], v[28:31]
	v_mfma_f32_16x16x32_bf16 v[20:23], v[152:155], v[192:195], v[20:23]
	v_mfma_f32_16x16x32_bf16 v[12:15], v[140:143], v[200:203], v[12:15]
	v_mfma_f32_16x16x32_bf16 v[4:7], v[152:155], v[200:203], v[4:7]
	v_mfma_f32_16x16x32_bf16 v[60:63], v[148:151], v[180:183], v[60:63]
	v_mfma_f32_16x16x32_bf16 v[52:55], v[156:159], v[180:183], v[52:55]
	v_mfma_f32_16x16x32_bf16 v[44:47], v[148:151], v[188:191], v[44:47]
	v_mfma_f32_16x16x32_bf16 v[36:39], v[156:159], v[188:191], v[36:39]
	v_mfma_f32_16x16x32_bf16 v[28:31], v[148:151], v[196:199], v[28:31]
	v_mfma_f32_16x16x32_bf16 v[20:23], v[156:159], v[196:199], v[20:23]
	v_mfma_f32_16x16x32_bf16 v[12:15], v[148:151], v[204:207], v[12:15]
	v_mfma_f32_16x16x32_bf16 v[4:7], v[156:159], v[204:207], v[4:7]
	v_mfma_f32_16x16x32_bf16 v[56:59], v[160:163], v[176:179], v[56:59]
	v_mfma_f32_16x16x32_bf16 v[48:51], v[168:171], v[176:179], v[48:51]
	v_mfma_f32_16x16x32_bf16 v[40:43], v[160:163], v[184:187], v[40:43]
	v_mfma_f32_16x16x32_bf16 v[32:35], v[168:171], v[184:187], v[32:35]
	v_mfma_f32_16x16x32_bf16 v[24:27], v[160:163], v[192:195], v[24:27]
	v_mfma_f32_16x16x32_bf16 v[16:19], v[168:171], v[192:195], v[16:19]
	v_mfma_f32_16x16x32_bf16 v[8:11], v[160:163], v[200:203], v[8:11]
	v_mfma_f32_16x16x32_bf16 v[0:3], v[168:171], v[200:203], v[0:3]
	v_mfma_f32_16x16x32_bf16 v[56:59], v[164:167], v[180:183], v[56:59]
	v_mfma_f32_16x16x32_bf16 v[48:51], v[172:175], v[180:183], v[48:51]
	v_mfma_f32_16x16x32_bf16 v[40:43], v[164:167], v[188:191], v[40:43]
	v_mfma_f32_16x16x32_bf16 v[32:35], v[172:175], v[188:191], v[32:35]
	v_mfma_f32_16x16x32_bf16 v[24:27], v[164:167], v[196:199], v[24:27]
	v_mfma_f32_16x16x32_bf16 v[16:19], v[172:175], v[196:199], v[16:19]
	v_mfma_f32_16x16x32_bf16 v[8:11], v[164:167], v[204:207], v[8:11]
	v_mfma_f32_16x16x32_bf16 v[0:3], v[172:175], v[204:207], v[0:3]
	s_barrier
	s_add_i32 s8, 0, 0x18000
	s_add_i32 s37, 0, 0x1c000
	v_add_u32_e32 v156, s8, v145
	v_add_u32_e32 v172, s37, v145
	ds_read_b128 v[140:143], v156
	ds_read_b128 v[148:151], v156 offset:1024
	ds_read_b128 v[152:155], v156 offset:2048
	ds_read_b128 v[156:159], v156 offset:3072
	ds_read_b128 v[160:163], v172
	ds_read_b128 v[164:167], v172 offset:1024
	ds_read_b128 v[168:171], v172 offset:2048
	ds_read_b128 v[172:175], v172 offset:3072
	s_add_u32 s64, s64, 0x40000
	s_addc_u32 s65, s65, 0
	s_mov_b32 m0, s20
	v_lshl_add_u64 v[228:229], s[64:65], 0, v[134:135]
	ds_read_b128 v[176:179], v147 offset:32768
	ds_read_b128 v[180:183], v147 offset:33792
	ds_read_b128 v[184:187], v147 offset:34816
	ds_read_b128 v[188:191], v147 offset:35840
	ds_read_b128 v[192:195], v147 offset:36864
	ds_read_b128 v[196:199], v147 offset:37888
	ds_read_b128 v[200:203], v147 offset:38912
	ds_read_b128 v[204:207], v147 offset:39936
	global_load_lds_dwordx4 v[228:229], off
	v_lshl_add_u64 v[228:229], s[64:65], 0, v[132:133]
	s_mov_b32 m0, s21
	s_nop 0
	global_load_lds_dwordx4 v[228:229], off
	s_nop 0
	s_waitcnt vmcnt(8)
	s_waitcnt lgkmcnt(0)
	s_barrier
	s_waitcnt lgkmcnt(0)
	v_mfma_f32_16x16x32_bf16 v[124:127], v[140:143], v[176:179], v[124:127]
	v_mfma_f32_16x16x32_bf16 v[116:119], v[152:155], v[176:179], v[116:119]
	v_mfma_f32_16x16x32_bf16 v[108:111], v[140:143], v[184:187], v[108:111]
	v_mfma_f32_16x16x32_bf16 v[100:103], v[152:155], v[184:187], v[100:103]
	v_mfma_f32_16x16x32_bf16 v[92:95], v[140:143], v[192:195], v[92:95]
	v_mfma_f32_16x16x32_bf16 v[84:87], v[152:155], v[192:195], v[84:87]
	v_mfma_f32_16x16x32_bf16 v[76:79], v[140:143], v[200:203], v[76:79]
	v_mfma_f32_16x16x32_bf16 v[68:71], v[152:155], v[200:203], v[68:71]
	v_mfma_f32_16x16x32_bf16 v[124:127], v[148:151], v[180:183], v[124:127]
	v_mfma_f32_16x16x32_bf16 v[116:119], v[156:159], v[180:183], v[116:119]
	v_mfma_f32_16x16x32_bf16 v[108:111], v[148:151], v[188:191], v[108:111]
	v_mfma_f32_16x16x32_bf16 v[100:103], v[156:159], v[188:191], v[100:103]
	v_mfma_f32_16x16x32_bf16 v[92:95], v[148:151], v[196:199], v[92:95]
	v_mfma_f32_16x16x32_bf16 v[84:87], v[156:159], v[196:199], v[84:87]
	v_mfma_f32_16x16x32_bf16 v[76:79], v[148:151], v[204:207], v[76:79]
	v_mfma_f32_16x16x32_bf16 v[68:71], v[156:159], v[204:207], v[68:71]
	v_mfma_f32_16x16x32_bf16 v[120:123], v[160:163], v[176:179], v[120:123]
	v_mfma_f32_16x16x32_bf16 v[112:115], v[168:171], v[176:179], v[112:115]
	v_mfma_f32_16x16x32_bf16 v[104:107], v[160:163], v[184:187], v[104:107]
	v_mfma_f32_16x16x32_bf16 v[96:99], v[168:171], v[184:187], v[96:99]
	v_mfma_f32_16x16x32_bf16 v[88:91], v[160:163], v[192:195], v[88:91]
	v_mfma_f32_16x16x32_bf16 v[80:83], v[168:171], v[192:195], v[80:83]
	v_mfma_f32_16x16x32_bf16 v[72:75], v[160:163], v[200:203], v[72:75]
	v_mfma_f32_16x16x32_bf16 v[64:67], v[168:171], v[200:203], v[64:67]
	v_mfma_f32_16x16x32_bf16 v[120:123], v[164:167], v[180:183], v[120:123]
	v_mfma_f32_16x16x32_bf16 v[112:115], v[172:175], v[180:183], v[112:115]
	v_mfma_f32_16x16x32_bf16 v[104:107], v[164:167], v[188:191], v[104:107]
	v_mfma_f32_16x16x32_bf16 v[96:99], v[172:175], v[188:191], v[96:99]
	v_mfma_f32_16x16x32_bf16 v[88:91], v[164:167], v[196:199], v[88:91]
	v_mfma_f32_16x16x32_bf16 v[80:83], v[172:175], v[196:199], v[80:83]
	v_mfma_f32_16x16x32_bf16 v[72:75], v[164:167], v[204:207], v[72:75]
	v_mfma_f32_16x16x32_bf16 v[64:67], v[172:175], v[204:207], v[64:67]
	s_barrier
; #define PG8_STAGE(bufoff, gbase, voff) do { _Pragma("unroll") for (int _i = 0; _i < 2; ++_i) \
;         __builtin_amdgcn_global_load_lds((const unsigned*)((const char*)(gbase) + (voff)[_i]), (PG8_LAS unsigned*)(lds + (bufoff) + ldsw + _i * 8192), 16, 0, 0); } while (0)
; #define PG8_LDA(dst, b, h) do { _Pragma("unroll") for (int m = 0; m < 4; ++m) _Pragma("unroll") for (int k = 0; k < 2; ++k) dst[m][k] = *(const PG8_LAS bf16x8*)(lds + PG8_SA(b, h) + aoff + m * 2048 + k * 1024); } while (0)
; #define PG8_MMA(ai, bj, At, Bt) do { __builtin_amdgcn_s_setprio(1); _Pragma("unroll") for (int m = 0; m < 4; ++m) _Pragma("unroll") for (int n = 0; n < 2; ++n) _Pragma("unroll") for (int k = 0; k < 2; ++k) \
;         acc[ai][bj][m][n] = __builtin_amdgcn_mfma_f32_16x16x32_bf16(Bt[n][k], At[m][k], acc[ai][bj][m][n], 0, 0, 0); __builtin_amdgcn_s_setprio(0); } while (0)
; #define PG8_WAIT_V(n) asm volatile("s_waitcnt vmcnt(" #n ")" ::: "memory")
; #define PG8_WAIT_L(n) asm volatile("s_waitcnt lgkmcnt(" #n ")" ::: "memory")
; #define PG8_BAR __builtin_amdgcn_s_barrier()
; #define PG8_SCHED __builtin_amdgcn_sched_barrier(0)
; template <class Epi, class Sched, bool ALIGN_EPI = false, bool SP2 = false>
; __device__ __forceinline__ void gemm_phase(PG8_LAS unsigned char* lds, const Gemm g, const Sched& S, const Epi& E) {
;     ...
;             PG8_LDA(At, 1, 1); PG8_STAGE(PG8_SB(1, 0), b3, voffB); PG8_STAGE(PG8_SB(1, 1), b3 + hstep, voffB); PG8_STAGE(PG8_SA(1, 0), a3, voffA);
;             PG8_WAIT_V(8); PG8_WAIT_L(0); PG8_BAR; PG8_MMA(1, 0, At, B0); PG8_MMA(1, 1, At, B1); PG8_BAR; PG8_SCHED;
	s_add_i32 s8, s8, s17
	v_lshl_add_u64 v[208:209], v[208:209], 0, s[90:91]
	s_mov_b32 m0, s8
	ds_read_b128 v[176:179], v147 offset:49152
	ds_read_b128 v[180:183], v147 offset:50176
	ds_read_b128 v[184:187], v147 offset:51200
	ds_read_b128 v[188:191], v147 offset:52224
	ds_read_b128 v[192:195], v147 offset:53248
	ds_read_b128 v[196:199], v147 offset:54272
	ds_read_b128 v[200:203], v147 offset:55296
	ds_read_b128 v[204:207], v147 offset:56320
	global_load_lds_dwordx4 v[208:209], off
	s_add_i32 m0, s8, 0x2000
	s_add_u32 s58, s58, 0x40080
	v_lshl_add_u64 v[208:209], v[210:211], 0, s[90:91]
	s_addc_u32 s59, s59, 0
	s_add_i32 s8, s37, s17
	global_load_lds_dwordx4 v[208:209], off
	v_lshl_add_u64 v[208:209], s[58:59], 0, v[128:129]
	s_mov_b32 m0, s8
	s_nop 0
	global_load_lds_dwordx4 v[208:209], off
	v_lshl_add_u64 v[208:209], s[58:59], 0, v[130:131]
	s_add_i32 m0, s8, 0x2000
	s_nop 0
	global_load_lds_dwordx4 v[208:209], off
	v_lshl_add_u64 v[208:209], v[214:215], 0, s[90:91]
	s_mov_b32 m0, s22
	s_nop 0
	global_load_lds_dwordx4 v[208:209], off
	v_lshl_add_u64 v[208:209], v[222:223], 0, s[90:91]
	s_mov_b32 m0, s23
	s_nop 0
	global_load_lds_dwordx4 v[208:209], off
	s_waitcnt vmcnt(8)
	s_waitcnt lgkmcnt(0)
	s_barrier
	s_waitcnt lgkmcnt(0)
	v_mfma_f32_16x16x32_bf16 v[60:63], v[140:143], v[176:179], v[60:63]
	v_mfma_f32_16x16x32_bf16 v[52:55], v[152:155], v[176:179], v[52:55]
	v_mfma_f32_16x16x32_bf16 v[44:47], v[140:143], v[184:187], v[44:47]
	v_mfma_f32_16x16x32_bf16 v[36:39], v[152:155], v[184:187], v[36:39]
	v_mfma_f32_16x16x32_bf16 v[28:31], v[140:143], v[192:195], v[28:31]
	v_mfma_f32_16x16x32_bf16 v[20:23], v[152:155], v[192:195], v[20:23]
	v_mfma_f32_16x16x32_bf16 v[12:15], v[140:143], v[200:203], v[12:15]
	v_mfma_f32_16x16x32_bf16 v[4:7], v[152:155], v[200:203], v[4:7]
	v_mfma_f32_16x16x32_bf16 v[60:63], v[148:151], v[180:183], v[60:63]
	v_mfma_f32_16x16x32_bf16 v[52:55], v[156:159], v[180:183], v[52:55]
	v_mfma_f32_16x16x32_bf16 v[44:47], v[148:151], v[188:191], v[44:47]
	v_mfma_f32_16x16x32_bf16 v[36:39], v[156:159], v[188:191], v[36:39]
	v_mfma_f32_16x16x32_bf16 v[28:31], v[148:151], v[196:199], v[28:31]
	v_mfma_f32_16x16x32_bf16 v[20:23], v[156:159], v[196:199], v[20:23]
	v_mfma_f32_16x16x32_bf16 v[12:15], v[148:151], v[204:207], v[12:15]
	v_mfma_f32_16x16x32_bf16 v[4:7], v[156:159], v[204:207], v[4:7]
	v_mfma_f32_16x16x32_bf16 v[56:59], v[160:163], v[176:179], v[56:59]
	v_mfma_f32_16x16x32_bf16 v[48:51], v[168:171], v[176:179], v[48:51]
	v_mfma_f32_16x16x32_bf16 v[40:43], v[160:163], v[184:187], v[40:43]
	v_mfma_f32_16x16x32_bf16 v[32:35], v[168:171], v[184:187], v[32:35]
	v_mfma_f32_16x16x32_bf16 v[24:27], v[160:163], v[192:195], v[24:27]
	v_mfma_f32_16x16x32_bf16 v[16:19], v[168:171], v[192:195], v[16:19]
	v_mfma_f32_16x16x32_bf16 v[8:11], v[160:163], v[200:203], v[8:11]
	v_mfma_f32_16x16x32_bf16 v[0:3], v[168:171], v[200:203], v[0:3]
	v_mfma_f32_16x16x32_bf16 v[56:59], v[164:167], v[180:183], v[56:59]
	v_mfma_f32_16x16x32_bf16 v[48:51], v[172:175], v[180:183], v[48:51]
	v_mfma_f32_16x16x32_bf16 v[40:43], v[164:167], v[188:191], v[40:43]
	v_mfma_f32_16x16x32_bf16 v[32:35], v[172:175], v[188:191], v[32:35]
	v_mfma_f32_16x16x32_bf16 v[24:27], v[164:167], v[196:199], v[24:27]
	v_mfma_f32_16x16x32_bf16 v[16:19], v[172:175], v[196:199], v[16:19]
	v_mfma_f32_16x16x32_bf16 v[8:11], v[164:167], v[204:207], v[8:11]
	v_mfma_f32_16x16x32_bf16 v[0:3], v[172:175], v[204:207], v[0:3]
	s_barrier
	s_add_i32 s36, s36, 2
	s_add_u32 s66, s66, 0x100
	s_addc_u32 s67, s67, 0
	s_add_u32 s34, s34, 0x100
	s_addc_u32 s35, s35, 0
	s_cmp_gt_u32 s36, 13
	s_cbranch_scc0 .LBB0_813
	s_setprio 0
	s_and_b64 vcc, exec, s[46:47]
	s_cbranch_vccz .LBB0_816
	s_barrier

; #define PG8_STAGE(bufoff, gbase, voff) do { _Pragma("unroll") for (int _i = 0; _i < 2; ++_i) \
;         __builtin_amdgcn_global_load_lds((const unsigned*)((const char*)(gbase) + (voff)[_i]), (PG8_LAS unsigned*)(lds + (bufoff) + ldsw + _i * 8192), 16, 0, 0); } while (0)
; #define PG8_LDA(dst, b, h) do { _Pragma("unroll") for (int m = 0; m < 4; ++m) _Pragma("unroll") for (int k = 0; k < 2; ++k) dst[m][k] = *(const PG8_LAS bf16x8*)(lds + PG8_SA(b, h) + aoff + m * 2048 + k * 1024); } while (0)
; #define PG8_LDB(dst, b, h) do { _Pragma("unroll") for (int n = 0; n < 2; ++n) _Pragma("unroll") for (int k = 0; k < 2; ++k) dst[n][k] = *(const PG8_LAS bf16x8*)(lds + PG8_SB(b, h) + boff + n * 2048 + k * 1024); } while (0)
; #define PG8_MMA(ai, bj, At, Bt) do { __builtin_amdgcn_s_setprio(1); _Pragma("unroll") for (int m = 0; m < 4; ++m) _Pragma("unroll") for (int n = 0; n < 2; ++n) _Pragma("unroll") for (int k = 0; k < 2; ++k) \
;         acc[ai][bj][m][n] = __builtin_amdgcn_mfma_f32_16x16x32_bf16(Bt[n][k], At[m][k], acc[ai][bj][m][n], 0, 0, 0); __builtin_amdgcn_s_setprio(0); } while (0)
; #define PG8_WAIT_V(n) asm volatile("s_waitcnt vmcnt(" #n ")" ::: "memory")
; #define PG8_WAIT_L(n) asm volatile("s_waitcnt lgkmcnt(" #n ")" ::: "memory")
; #define PG8_BAR __builtin_amdgcn_s_barrier()
; #define PG8_SCHED __builtin_amdgcn_sched_barrier(0)
; template <class Epi, class Sched, bool ALIGN_EPI = false, bool SP2 = false>
; __device__ __forceinline__ void gemm_phase(PG8_LAS unsigned char* lds, const Gemm g, const Sched& S, const Epi& E) {
;     ...
;             const bool last = (t == nt - 2);
;             const char* a1 = cA + (size_t)(t + 1) * kstep;
;             const char* a2 = last ? nA : cA + (size_t)(t + 2) * kstep; const char* b2 = last ? nB : cB + (size_t)(t + 2) * kstep;
;             const char* a3 = a2 + kstep; const char* b3 = b2 + kstep;
;             if (last && has_next) S.a_ready(nxt);
;             if constexpr (SP2) {
;             PG8_LDB(B0, 0, 0); PG8_LDB(B1, 0, 1); PG8_SCHED; PG8_LDA(At, 0, 0); PG8_STAGE(PG8_SA(1, 1), a1 + hstep, voffA);
;             PG8_WAIT_V(8); PG8_WAIT_L(0); PG8_BAR; PG8_MMA(0, 0, At, B0); PG8_MMA(0, 1, At, B1); PG8_BAR; PG8_SCHED;
;             PG8_LDA(At, 0, 1); PG8_STAGE(PG8_SB(0, 0), b2, voffB); PG8_STAGE(PG8_SB(0, 1), b2 + hstep, voffB); PG8_STAGE(PG8_SA(0, 0), a2, voffA);
.Lsp_4:
.LBB0_957:
	s_add_u32 s44, s96, 0x100
	s_addc_u32 s45, s97, 0
	s_add_i32 s8, 0, 0x10000
	s_cmp_eq_u32 s70, 40
	s_cselect_b32 s65, s67, s45
	s_cselect_b32 s64, s66, s44
	s_cselect_b32 s47, s73, s37
	s_cselect_b32 s46, s72, s36
	s_add_i32 s88, 0, 0x14000
	v_add_u32_e32 v142, s8, v185
	v_add_u32_e32 v168, s88, v185
	ds_read_b128 v[130:133], v142
	ds_read_b128 v[134:137], v142 offset:1024
	ds_read_b128 v[138:141], v142 offset:2048
	ds_read_b128 v[142:145], v142 offset:3072
	ds_read_b128 v[156:159], v168
	ds_read_b128 v[160:163], v168 offset:1024
	ds_read_b128 v[164:167], v168 offset:2048
	ds_read_b128 v[168:171], v168 offset:3072
	v_lshl_add_u64 v[208:209], s[96:97], 0, v[152:153]
	s_add_i32 m0, s15, 0xc000
	ds_read_b128 v[172:175], v191
	ds_read_b128 v[176:179], v191 offset:1024
	ds_read_b128 v[180:183], v191 offset:2048
	ds_read_b128 v[186:189], v191 offset:3072
	ds_read_b128 v[192:195], v191 offset:4096
	ds_read_b128 v[196:199], v191 offset:5120
	ds_read_b128 v[200:203], v191 offset:6144
	ds_read_b128 v[204:207], v191 offset:7168
	global_load_lds_dwordx4 v[208:209], off
	v_lshl_add_u64 v[208:209], s[96:97], 0, v[154:155]
	s_add_i32 m0, s15, 0xe000
	s_nop 0
	global_load_lds_dwordx4 v[208:209], off
	s_nop 0
	s_waitcnt vmcnt(8)
	s_waitcnt lgkmcnt(0)
	s_barrier
	s_waitcnt lgkmcnt(0)
	v_mfma_f32_16x16x32_bf16 v[124:127], v[130:133], v[172:175], v[124:127]
	v_mfma_f32_16x16x32_bf16 v[120:123], v[138:141], v[172:175], v[120:123]
	v_mfma_f32_16x16x32_bf16 v[108:111], v[130:133], v[180:183], v[108:111]
	v_mfma_f32_16x16x32_bf16 v[104:107], v[138:141], v[180:183], v[104:107]
	v_mfma_f32_16x16x32_bf16 v[92:95], v[130:133], v[192:195], v[92:95]
	v_mfma_f32_16x16x32_bf16 v[88:91], v[138:141], v[192:195], v[88:91]
	v_mfma_f32_16x16x32_bf16 v[76:79], v[130:133], v[200:203], v[76:79]
	v_mfma_f32_16x16x32_bf16 v[72:75], v[138:141], v[200:203], v[72:75]
	v_mfma_f32_16x16x32_bf16 v[124:127], v[134:137], v[176:179], v[124:127]
	v_mfma_f32_16x16x32_bf16 v[120:123], v[142:145], v[176:179], v[120:123]
	v_mfma_f32_16x16x32_bf16 v[108:111], v[134:137], v[186:189], v[108:111]
	v_mfma_f32_16x16x32_bf16 v[104:107], v[142:145], v[186:189], v[104:107]
	v_mfma_f32_16x16x32_bf16 v[92:95], v[134:137], v[196:199], v[92:95]
	v_mfma_f32_16x16x32_bf16 v[88:91], v[142:145], v[196:199], v[88:91]
	v_mfma_f32_16x16x32_bf16 v[76:79], v[134:137], v[204:207], v[76:79]
	v_mfma_f32_16x16x32_bf16 v[72:75], v[142:145], v[204:207], v[72:75]
	v_mfma_f32_16x16x32_bf16 v[116:119], v[156:159], v[172:175], v[116:119]
	v_mfma_f32_16x16x32_bf16 v[112:115], v[164:167], v[172:175], v[112:115]
	v_mfma_f32_16x16x32_bf16 v[100:103], v[156:159], v[180:183], v[100:103]
	v_mfma_f32_16x16x32_bf16 v[96:99], v[164:167], v[180:183], v[96:99]
	v_mfma_f32_16x16x32_bf16 v[84:87], v[156:159], v[192:195], v[84:87]
	v_mfma_f32_16x16x32_bf16 v[80:83], v[164:167], v[192:195], v[80:83]
	v_mfma_f32_16x16x32_bf16 v[68:71], v[156:159], v[200:203], v[68:71]
	v_mfma_f32_16x16x32_bf16 v[64:67], v[164:167], v[200:203], v[64:67]
	v_mfma_f32_16x16x32_bf16 v[116:119], v[160:163], v[176:179], v[116:119]
	v_mfma_f32_16x16x32_bf16 v[112:115], v[168:171], v[176:179], v[112:115]
	v_mfma_f32_16x16x32_bf16 v[100:103], v[160:163], v[186:189], v[100:103]
	v_mfma_f32_16x16x32_bf16 v[96:99], v[168:171], v[186:189], v[96:99]
	v_mfma_f32_16x16x32_bf16 v[84:87], v[160:163], v[196:199], v[84:87]
	v_mfma_f32_16x16x32_bf16 v[80:83], v[168:171], v[196:199], v[80:83]
	v_mfma_f32_16x16x32_bf16 v[68:71], v[160:163], v[204:207], v[68:71]
	v_mfma_f32_16x16x32_bf16 v[64:67], v[168:171], v[204:207], v[64:67]
	s_barrier
	s_add_i32 s8, s8, s14
	v_lshl_add_u64 v[208:209], s[46:47], 0, v[128:129]
	s_mov_b32 m0, s8
	ds_read_b128 v[172:175], v191 offset:16384
	ds_read_b128 v[176:179], v191 offset:17408
	ds_read_b128 v[180:183], v191 offset:18432
	ds_read_b128 v[186:189], v191 offset:19456
	ds_read_b128 v[192:195], v191 offset:20480
	ds_read_b128 v[196:199], v191 offset:21504
	ds_read_b128 v[200:203], v191 offset:22528
	ds_read_b128 v[204:207], v191 offset:23552
	global_load_lds_dwordx4 v[208:209], off
	s_add_i32 m0, s8, 0x2000
	s_add_u32 s84, s46, 0xb0000
	v_lshl_add_u64 v[210:211], s[46:47], 0, v[146:147]
	s_addc_u32 s85, s47, 0
	s_add_i32 s8, s88, s14
	global_load_lds_dwordx4 v[210:211], off
	v_lshl_add_u64 v[214:215], s[84:85], 0, v[128:129]
	s_mov_b32 m0, s8
	v_lshl_add_u64 v[222:223], s[64:65], 0, v[148:149]
	global_load_lds_dwordx4 v[214:215], off
	v_lshl_add_u64 v[214:215], s[84:85], 0, v[146:147]
	s_add_i32 m0, s8, 0x2000
	s_nop 0
	global_load_lds_dwordx4 v[214:215], off
	v_lshl_add_u64 v[214:215], s[64:65], 0, v[150:151]
	s_mov_b32 m0, s15
	s_nop 0
	global_load_lds_dwordx4 v[214:215], off
	s_mov_b32 m0, s18
	s_nop 0
	global_load_lds_dwordx4 v[222:223], off
	s_nop 0
	s_waitcnt vmcnt(8)
	s_waitcnt lgkmcnt(0)
	s_barrier
; #define PG8_STAGE(bufoff, gbase, voff) do { _Pragma("unroll") for (int _i = 0; _i < 2; ++_i) \
;         __builtin_amdgcn_global_load_lds((const unsigned*)((const char*)(gbase) + (voff)[_i]), (PG8_LAS unsigned*)(lds + (bufoff) + ldsw + _i * 8192), 16, 0, 0); } while (0)
; #define PG8_LDA(dst, b, h) do { _Pragma("unroll") for (int m = 0; m < 4; ++m) _Pragma("unroll") for (int k = 0; k < 2; ++k) dst[m][k] = *(const PG8_LAS bf16x8*)(lds + PG8_SA(b, h) + aoff + m * 2048 + k * 1024); } while (0)
; #define PG8_LDB(dst, b, h) do { _Pragma("unroll") for (int n = 0; n < 2; ++n) _Pragma("unroll") for (int k = 0; k < 2; ++k) dst[n][k] = *(const PG8_LAS bf16x8*)(lds + PG8_SB(b, h) + boff + n * 2048 + k * 1024); } while (0)
; #define PG8_MMA(ai, bj, At, Bt) do { __builtin_amdgcn_s_setprio(1); _Pragma("unroll") for (int m = 0; m < 4; ++m) _Pragma("unroll") for (int n = 0; n < 2; ++n) _Pragma("unroll") for (int k = 0; k < 2; ++k) \
;         acc[ai][bj][m][n] = __builtin_amdgcn_mfma_f32_16x16x32_bf16(Bt[n][k], At[m][k], acc[ai][bj][m][n], 0, 0, 0); __builtin_amdgcn_s_setprio(0); } while (0)
; #define PG8_WAIT_V(n) asm volatile("s_waitcnt vmcnt(" #n ")" ::: "memory")
; #define PG8_WAIT_L(n) asm volatile("s_waitcnt lgkmcnt(" #n ")" ::: "memory")
; #define PG8_BAR __builtin_amdgcn_s_barrier()
; #define PG8_SCHED __builtin_amdgcn_sched_barrier(0)
; template <class Epi, class Sched, bool ALIGN_EPI = false, bool SP2 = false>
; __device__ __forceinline__ void gemm_phase(PG8_LAS unsigned char* lds, const Gemm g, const Sched& S, const Epi& E) {
;     ...
;             PG8_WAIT_V(8); PG8_WAIT_L(0); PG8_BAR; PG8_MMA(1, 0, At, B0); PG8_MMA(1, 1, At, B1); PG8_BAR; PG8_SCHED;
;             PG8_LDB(B0, 1, 0); PG8_LDB(B1, 1, 1); PG8_SCHED; PG8_LDA(At, 1, 0); PG8_STAGE(PG8_SA(0, 1), a2 + hstep, voffA);
;             PG8_WAIT_V(8); PG8_WAIT_L(0); PG8_BAR; PG8_MMA(0, 0, At, B0); PG8_MMA(0, 1, At, B1); PG8_BAR; PG8_SCHED;
	s_waitcnt lgkmcnt(0)
	v_mfma_f32_16x16x32_bf16 v[60:63], v[130:133], v[172:175], v[60:63]
	v_mfma_f32_16x16x32_bf16 v[56:59], v[138:141], v[172:175], v[56:59]
	v_mfma_f32_16x16x32_bf16 v[44:47], v[130:133], v[180:183], v[44:47]
	v_mfma_f32_16x16x32_bf16 v[40:43], v[138:141], v[180:183], v[40:43]
	v_mfma_f32_16x16x32_bf16 v[28:31], v[130:133], v[192:195], v[28:31]
	v_mfma_f32_16x16x32_bf16 v[24:27], v[138:141], v[192:195], v[24:27]
	v_mfma_f32_16x16x32_bf16 v[12:15], v[130:133], v[200:203], v[12:15]
	v_mfma_f32_16x16x32_bf16 v[8:11], v[138:141], v[200:203], v[8:11]
	v_mfma_f32_16x16x32_bf16 v[60:63], v[134:137], v[176:179], v[60:63]
	v_mfma_f32_16x16x32_bf16 v[56:59], v[142:145], v[176:179], v[56:59]
	v_mfma_f32_16x16x32_bf16 v[44:47], v[134:137], v[186:189], v[44:47]
	v_mfma_f32_16x16x32_bf16 v[40:43], v[142:145], v[186:189], v[40:43]
	v_mfma_f32_16x16x32_bf16 v[28:31], v[134:137], v[196:199], v[28:31]
	v_mfma_f32_16x16x32_bf16 v[24:27], v[142:145], v[196:199], v[24:27]
	v_mfma_f32_16x16x32_bf16 v[12:15], v[134:137], v[204:207], v[12:15]
	v_mfma_f32_16x16x32_bf16 v[8:11], v[142:145], v[204:207], v[8:11]
	v_mfma_f32_16x16x32_bf16 v[52:55], v[156:159], v[172:175], v[52:55]
	v_mfma_f32_16x16x32_bf16 v[48:51], v[164:167], v[172:175], v[48:51]
	v_mfma_f32_16x16x32_bf16 v[36:39], v[156:159], v[180:183], v[36:39]
	v_mfma_f32_16x16x32_bf16 v[32:35], v[164:167], v[180:183], v[32:35]
	v_mfma_f32_16x16x32_bf16 v[20:23], v[156:159], v[192:195], v[20:23]
	v_mfma_f32_16x16x32_bf16 v[16:19], v[164:167], v[192:195], v[16:19]
	v_mfma_f32_16x16x32_bf16 v[4:7], v[156:159], v[200:203], v[4:7]
	v_mfma_f32_16x16x32_bf16 v[0:3], v[164:167], v[200:203], v[0:3]
	v_mfma_f32_16x16x32_bf16 v[52:55], v[160:163], v[176:179], v[52:55]
	v_mfma_f32_16x16x32_bf16 v[48:51], v[168:171], v[176:179], v[48:51]
	v_mfma_f32_16x16x32_bf16 v[36:39], v[160:163], v[186:189], v[36:39]
	v_mfma_f32_16x16x32_bf16 v[32:35], v[168:171], v[186:189], v[32:35]
	v_mfma_f32_16x16x32_bf16 v[20:23], v[160:163], v[196:199], v[20:23]
	v_mfma_f32_16x16x32_bf16 v[16:19], v[168:171], v[196:199], v[16:19]
	v_mfma_f32_16x16x32_bf16 v[4:7], v[160:163], v[204:207], v[4:7]
	v_mfma_f32_16x16x32_bf16 v[0:3], v[168:171], v[204:207], v[0:3]
	s_barrier
	s_add_i32 s8, 0, 0x18000
	s_add_i32 s84, 0, 0x1c000
	v_add_u32_e32 v142, s8, v185
	v_add_u32_e32 v168, s84, v185
	ds_read_b128 v[130:133], v142
	ds_read_b128 v[134:137], v142 offset:1024
	ds_read_b128 v[138:141], v142 offset:2048
	ds_read_b128 v[142:145], v142 offset:3072
	ds_read_b128 v[156:159], v168
	ds_read_b128 v[160:163], v168 offset:1024
	ds_read_b128 v[164:167], v168 offset:2048
	ds_read_b128 v[168:171], v168 offset:3072
	s_add_u32 s64, s64, 0xb0000
	s_addc_u32 s65, s65, 0
	s_mov_b32 m0, s19
	v_lshl_add_u64 v[228:229], s[64:65], 0, v[150:151]
	ds_read_b128 v[172:175], v191 offset:32768
	ds_read_b128 v[176:179], v191 offset:33792
	ds_read_b128 v[180:183], v191 offset:34816
	ds_read_b128 v[186:189], v191 offset:35840
	ds_read_b128 v[192:195], v191 offset:36864
	ds_read_b128 v[196:199], v191 offset:37888
	ds_read_b128 v[200:203], v191 offset:38912
	ds_read_b128 v[204:207], v191 offset:39936
	global_load_lds_dwordx4 v[228:229], off
	v_lshl_add_u64 v[228:229], s[64:65], 0, v[148:149]
	s_mov_b32 m0, s20
	s_nop 0
	global_load_lds_dwordx4 v[228:229], off
	s_nop 0
	s_waitcnt vmcnt(8)
	s_waitcnt lgkmcnt(0)
	s_barrier
	s_waitcnt lgkmcnt(0)
	v_mfma_f32_16x16x32_bf16 v[124:127], v[130:133], v[172:175], v[124:127]
	v_mfma_f32_16x16x32_bf16 v[120:123], v[138:141], v[172:175], v[120:123]
	v_mfma_f32_16x16x32_bf16 v[108:111], v[130:133], v[180:183], v[108:111]
	v_mfma_f32_16x16x32_bf16 v[104:107], v[138:141], v[180:183], v[104:107]
	v_mfma_f32_16x16x32_bf16 v[92:95], v[130:133], v[192:195], v[92:95]
	v_mfma_f32_16x16x32_bf16 v[88:91], v[138:141], v[192:195], v[88:91]
	v_mfma_f32_16x16x32_bf16 v[76:79], v[130:133], v[200:203], v[76:79]
	v_mfma_f32_16x16x32_bf16 v[72:75], v[138:141], v[200:203], v[72:75]
	v_mfma_f32_16x16x32_bf16 v[124:127], v[134:137], v[176:179], v[124:127]
	v_mfma_f32_16x16x32_bf16 v[120:123], v[142:145], v[176:179], v[120:123]
	v_mfma_f32_16x16x32_bf16 v[108:111], v[134:137], v[186:189], v[108:111]
	v_mfma_f32_16x16x32_bf16 v[104:107], v[142:145], v[186:189], v[104:107]
	v_mfma_f32_16x16x32_bf16 v[92:95], v[134:137], v[196:199], v[92:95]
	v_mfma_f32_16x16x32_bf16 v[88:91], v[142:145], v[196:199], v[88:91]
	v_mfma_f32_16x16x32_bf16 v[76:79], v[134:137], v[204:207], v[76:79]
	v_mfma_f32_16x16x32_bf16 v[72:75], v[142:145], v[204:207], v[72:75]
	v_mfma_f32_16x16x32_bf16 v[116:119], v[156:159], v[172:175], v[116:119]
	v_mfma_f32_16x16x32_bf16 v[112:115], v[164:167], v[172:175], v[112:115]
	v_mfma_f32_16x16x32_bf16 v[100:103], v[156:159], v[180:183], v[100:103]
	v_mfma_f32_16x16x32_bf16 v[96:99], v[164:167], v[180:183], v[96:99]
	v_mfma_f32_16x16x32_bf16 v[84:87], v[156:159], v[192:195], v[84:87]
	v_mfma_f32_16x16x32_bf16 v[80:83], v[164:167], v[192:195], v[80:83]
	v_mfma_f32_16x16x32_bf16 v[68:71], v[156:159], v[200:203], v[68:71]
	v_mfma_f32_16x16x32_bf16 v[64:67], v[164:167], v[200:203], v[64:67]
	v_mfma_f32_16x16x32_bf16 v[116:119], v[160:163], v[176:179], v[116:119]
	v_mfma_f32_16x16x32_bf16 v[112:115], v[168:171], v[176:179], v[112:115]
	v_mfma_f32_16x16x32_bf16 v[100:103], v[160:163], v[186:189], v[100:103]
	v_mfma_f32_16x16x32_bf16 v[96:99], v[168:171], v[186:189], v[96:99]
	v_mfma_f32_16x16x32_bf16 v[84:87], v[160:163], v[196:199], v[84:87]
	v_mfma_f32_16x16x32_bf16 v[80:83], v[168:171], v[196:199], v[80:83]
	v_mfma_f32_16x16x32_bf16 v[68:71], v[160:163], v[204:207], v[68:71]
	v_mfma_f32_16x16x32_bf16 v[64:67], v[168:171], v[204:207], v[64:67]
	s_barrier
; #define PG8_STAGE(bufoff, gbase, voff) do { _Pragma("unroll") for (int _i = 0; _i < 2; ++_i) \
;         __builtin_amdgcn_global_load_lds((const unsigned*)((const char*)(gbase) + (voff)[_i]), (PG8_LAS unsigned*)(lds + (bufoff) + ldsw + _i * 8192), 16, 0, 0); } while (0)
; #define PG8_LDA(dst, b, h) do { _Pragma("unroll") for (int m = 0; m < 4; ++m) _Pragma("unroll") for (int k = 0; k < 2; ++k) dst[m][k] = *(const PG8_LAS bf16x8*)(lds + PG8_SA(b, h) + aoff + m * 2048 + k * 1024); } while (0)
; #define PG8_MMA(ai, bj, At, Bt) do { __builtin_amdgcn_s_setprio(1); _Pragma("unroll") for (int m = 0; m < 4; ++m) _Pragma("unroll") for (int n = 0; n < 2; ++n) _Pragma("unroll") for (int k = 0; k < 2; ++k) \
;         acc[ai][bj][m][n] = __builtin_amdgcn_mfma_f32_16x16x32_bf16(Bt[n][k], At[m][k], acc[ai][bj][m][n], 0, 0, 0); __builtin_amdgcn_s_setprio(0); } while (0)
; #define PG8_WAIT_V(n) asm volatile("s_waitcnt vmcnt(" #n ")" ::: "memory")
; #define PG8_WAIT_L(n) asm volatile("s_waitcnt lgkmcnt(" #n ")" ::: "memory")
; #define PG8_BAR __builtin_amdgcn_s_barrier()
; #define PG8_SCHED __builtin_amdgcn_sched_barrier(0)
; template <class Epi, class Sched, bool ALIGN_EPI = false, bool SP2 = false>
; __device__ __forceinline__ void gemm_phase(PG8_LAS unsigned char* lds, const Gemm g, const Sched& S, const Epi& E) {
;     ...
;             PG8_LDA(At, 1, 1); PG8_STAGE(PG8_SB(1, 0), b3, voffB); PG8_STAGE(PG8_SB(1, 1), b3 + hstep, voffB); PG8_STAGE(PG8_SA(1, 0), a3, voffA);
;             PG8_WAIT_V(8); PG8_WAIT_L(0); PG8_BAR; PG8_MMA(1, 0, At, B0); PG8_MMA(1, 1, At, B1); PG8_BAR; PG8_SCHED;
	s_add_i32 s8, s8, s14
	v_lshl_add_u64 v[208:209], v[208:209], 0, s[90:91]
	s_mov_b32 m0, s8
	ds_read_b128 v[172:175], v191 offset:49152
	ds_read_b128 v[176:179], v191 offset:50176
	ds_read_b128 v[180:183], v191 offset:51200
	ds_read_b128 v[186:189], v191 offset:52224
	ds_read_b128 v[192:195], v191 offset:53248
	ds_read_b128 v[196:199], v191 offset:54272
	ds_read_b128 v[200:203], v191 offset:55296
	ds_read_b128 v[204:207], v191 offset:56320
	global_load_lds_dwordx4 v[208:209], off
	s_add_i32 m0, s8, 0x2000
	s_add_u32 s46, s46, 0xb0080
	v_lshl_add_u64 v[208:209], v[210:211], 0, s[90:91]
	s_addc_u32 s47, s47, 0
	s_add_i32 s8, s84, s14
	global_load_lds_dwordx4 v[208:209], off
	v_lshl_add_u64 v[208:209], s[46:47], 0, v[128:129]
	s_mov_b32 m0, s8
	s_nop 0
	global_load_lds_dwordx4 v[208:209], off
	v_lshl_add_u64 v[208:209], s[46:47], 0, v[146:147]
	s_add_i32 m0, s8, 0x2000
	s_nop 0
	global_load_lds_dwordx4 v[208:209], off
	v_lshl_add_u64 v[208:209], v[214:215], 0, s[90:91]
	s_mov_b32 m0, s27
	s_nop 0
	global_load_lds_dwordx4 v[208:209], off
	v_lshl_add_u64 v[208:209], v[222:223], 0, s[90:91]
	s_mov_b32 m0, s28
	s_nop 0
	global_load_lds_dwordx4 v[208:209], off
	s_waitcnt vmcnt(8)
	s_waitcnt lgkmcnt(0)
	s_barrier
	s_waitcnt lgkmcnt(0)
	v_mfma_f32_16x16x32_bf16 v[60:63], v[130:133], v[172:175], v[60:63]
	v_mfma_f32_16x16x32_bf16 v[56:59], v[138:141], v[172:175], v[56:59]
	v_mfma_f32_16x16x32_bf16 v[44:47], v[130:133], v[180:183], v[44:47]
	v_mfma_f32_16x16x32_bf16 v[40:43], v[138:141], v[180:183], v[40:43]
	v_mfma_f32_16x16x32_bf16 v[28:31], v[130:133], v[192:195], v[28:31]
	v_mfma_f32_16x16x32_bf16 v[24:27], v[138:141], v[192:195], v[24:27]
	v_mfma_f32_16x16x32_bf16 v[12:15], v[130:133], v[200:203], v[12:15]
	v_mfma_f32_16x16x32_bf16 v[8:11], v[138:141], v[200:203], v[8:11]
	v_mfma_f32_16x16x32_bf16 v[60:63], v[134:137], v[176:179], v[60:63]
	v_mfma_f32_16x16x32_bf16 v[56:59], v[142:145], v[176:179], v[56:59]
	v_mfma_f32_16x16x32_bf16 v[44:47], v[134:137], v[186:189], v[44:47]
	v_mfma_f32_16x16x32_bf16 v[40:43], v[142:145], v[186:189], v[40:43]
	v_mfma_f32_16x16x32_bf16 v[28:31], v[134:137], v[196:199], v[28:31]
	v_mfma_f32_16x16x32_bf16 v[24:27], v[142:145], v[196:199], v[24:27]
	v_mfma_f32_16x16x32_bf16 v[12:15], v[134:137], v[204:207], v[12:15]
	v_mfma_f32_16x16x32_bf16 v[8:11], v[142:145], v[204:207], v[8:11]
	v_mfma_f32_16x16x32_bf16 v[52:55], v[156:159], v[172:175], v[52:55]
	v_mfma_f32_16x16x32_bf16 v[48:51], v[164:167], v[172:175], v[48:51]
	v_mfma_f32_16x16x32_bf16 v[36:39], v[156:159], v[180:183], v[36:39]
	v_mfma_f32_16x16x32_bf16 v[32:35], v[164:167], v[180:183], v[32:35]
	v_mfma_f32_16x16x32_bf16 v[20:23], v[156:159], v[192:195], v[20:23]
	v_mfma_f32_16x16x32_bf16 v[16:19], v[164:167], v[192:195], v[16:19]
	v_mfma_f32_16x16x32_bf16 v[4:7], v[156:159], v[200:203], v[4:7]
	v_mfma_f32_16x16x32_bf16 v[0:3], v[164:167], v[200:203], v[0:3]
	v_mfma_f32_16x16x32_bf16 v[52:55], v[160:163], v[176:179], v[52:55]
	v_mfma_f32_16x16x32_bf16 v[48:51], v[168:171], v[176:179], v[48:51]
	v_mfma_f32_16x16x32_bf16 v[36:39], v[160:163], v[186:189], v[36:39]
	v_mfma_f32_16x16x32_bf16 v[32:35], v[168:171], v[186:189], v[32:35]
	v_mfma_f32_16x16x32_bf16 v[20:23], v[160:163], v[196:199], v[20:23]
	v_mfma_f32_16x16x32_bf16 v[16:19], v[168:171], v[196:199], v[16:19]
	v_mfma_f32_16x16x32_bf16 v[4:7], v[160:163], v[204:207], v[4:7]
	v_mfma_f32_16x16x32_bf16 v[0:3], v[168:171], v[204:207], v[0:3]
	s_barrier
	s_add_i32 s70, s70, 2
	s_add_u32 s36, s36, 0x100
	s_addc_u32 s37, s37, 0
	s_cmp_gt_u32 s70, 41
	s_mov_b64 s[96:97], s[44:45]
	s_cbranch_scc0 .LBB0_957
	s_setprio 0
	s_and_b64 vcc, exec, s[58:59]
	s_cbranch_vccz .LBB0_960
	s_barrier

; #define PG8_STAGE(bufoff, gbase, voff) do { _Pragma("unroll") for (int _i = 0; _i < 2; ++_i) \
;         __builtin_amdgcn_global_load_lds((const unsigned*)((const char*)(gbase) + (voff)[_i]), (PG8_LAS unsigned*)(lds + (bufoff) + ldsw + _i * 8192), 16, 0, 0); } while (0)
; #define PG8_LDA(dst, b, h) do { _Pragma("unroll") for (int m = 0; m < 4; ++m) _Pragma("unroll") for (int k = 0; k < 2; ++k) dst[m][k] = *(const PG8_LAS bf16x8*)(lds + PG8_SA(b, h) + aoff + m * 2048 + k * 1024); } while (0)
; #define PG8_LDB(dst, b, h) do { _Pragma("unroll") for (int n = 0; n < 2; ++n) _Pragma("unroll") for (int k = 0; k < 2; ++k) dst[n][k] = *(const PG8_LAS bf16x8*)(lds + PG8_SB(b, h) + boff + n * 2048 + k * 1024); } while (0)
; #define PG8_MMA(ai, bj, At, Bt) do { __builtin_amdgcn_s_setprio(1); _Pragma("unroll") for (int m = 0; m < 4; ++m) _Pragma("unroll") for (int n = 0; n < 2; ++n) _Pragma("unroll") for (int k = 0; k < 2; ++k) \
;         acc[ai][bj][m][n] = __builtin_amdgcn_mfma_f32_16x16x32_bf16(Bt[n][k], At[m][k], acc[ai][bj][m][n], 0, 0, 0); __builtin_amdgcn_s_setprio(0); } while (0)
; #define PG8_WAIT_V(n) asm volatile("s_waitcnt vmcnt(" #n ")" ::: "memory")
; #define PG8_WAIT_L(n) asm volatile("s_waitcnt lgkmcnt(" #n ")" ::: "memory")
; #define PG8_BAR __builtin_amdgcn_s_barrier()
; #define PG8_SCHED __builtin_amdgcn_sched_barrier(0)
; template <class Epi, class Sched, bool ALIGN_EPI = false, bool SP2 = false>
; __device__ __forceinline__ void gemm_phase(PG8_LAS unsigned char* lds, const Gemm g, const Sched& S, const Epi& E) {
;     ...
;             const bool last = (t == nt - 2);
;             const char* a1 = cA + (size_t)(t + 1) * kstep;
;             const char* a2 = last ? nA : cA + (size_t)(t + 2) * kstep; const char* b2 = last ? nB : cB + (size_t)(t + 2) * kstep;
;             const char* a3 = a2 + kstep; const char* b3 = b2 + kstep;
;             if (last && has_next) S.a_ready(nxt);
;             if constexpr (SP2) {
;             PG8_LDB(B0, 0, 0); PG8_LDB(B1, 0, 1); PG8_SCHED; PG8_LDA(At, 0, 0); PG8_STAGE(PG8_SA(1, 1), a1 + hstep, voffA);
;             PG8_WAIT_V(8); PG8_WAIT_L(0); PG8_BAR; PG8_MMA(0, 0, At, B0); PG8_MMA(0, 1, At, B1); PG8_BAR; PG8_SCHED;
;             PG8_LDA(At, 0, 1); PG8_STAGE(PG8_SB(0, 0), b2, voffB); PG8_STAGE(PG8_SB(0, 1), b2 + hstep, voffB); PG8_STAGE(PG8_SA(0, 0), a2, voffA);
.Lsp_5:
.LBB0_995:
	s_add_u32 s42, s96, 0x100
	s_addc_u32 s43, s97, 0
	s_add_i32 s8, 0, 0x10000
	s_cmp_eq_u32 s84, 40
	s_cselect_b32 s65, s67, s43
	s_cselect_b32 s64, s66, s42
	s_cselect_b32 s47, s73, s37
	s_cselect_b32 s46, s72, s36
	s_add_i32 s85, 0, 0x14000
	v_add_u32_e32 v142, s8, v201
	v_add_u32_e32 v168, s85, v201
	ds_read_b128 v[130:133], v142
	ds_read_b128 v[134:137], v142 offset:1024
	ds_read_b128 v[138:141], v142 offset:2048
	ds_read_b128 v[142:145], v142 offset:3072
	ds_read_b128 v[156:159], v168
	ds_read_b128 v[160:163], v168 offset:1024
	ds_read_b128 v[164:167], v168 offset:2048
	ds_read_b128 v[168:171], v168 offset:3072
	v_lshl_add_u64 v[208:209], s[96:97], 0, v[152:153]
	s_add_i32 m0, s15, 0xc000
	ds_read_b128 v[172:175], v203
	ds_read_b128 v[176:179], v203 offset:1024
	ds_read_b128 v[180:183], v203 offset:2048
	ds_read_b128 v[184:187], v203 offset:3072
	ds_read_b128 v[188:191], v203 offset:4096
	ds_read_b128 v[192:195], v203 offset:5120
	ds_read_b128 v[196:199], v203 offset:6144
	ds_read_b128 v[204:207], v203 offset:7168
	global_load_lds_dwordx4 v[208:209], off
	v_lshl_add_u64 v[208:209], s[96:97], 0, v[154:155]
	s_add_i32 m0, s15, 0xe000
	s_nop 0
	global_load_lds_dwordx4 v[208:209], off
	s_waitcnt vmcnt(8)
	s_waitcnt lgkmcnt(0)
	s_barrier
	s_waitcnt lgkmcnt(0)
	v_mfma_f32_16x16x32_bf16 v[124:127], v[130:133], v[172:175], v[124:127]
	v_mfma_f32_16x16x32_bf16 v[120:123], v[138:141], v[172:175], v[120:123]
	v_mfma_f32_16x16x32_bf16 v[108:111], v[130:133], v[180:183], v[108:111]
	v_mfma_f32_16x16x32_bf16 v[104:107], v[138:141], v[180:183], v[104:107]
	v_mfma_f32_16x16x32_bf16 v[92:95], v[130:133], v[188:191], v[92:95]
	v_mfma_f32_16x16x32_bf16 v[88:91], v[138:141], v[188:191], v[88:91]
	v_mfma_f32_16x16x32_bf16 v[76:79], v[130:133], v[196:199], v[76:79]
	v_mfma_f32_16x16x32_bf16 v[72:75], v[138:141], v[196:199], v[72:75]
	v_mfma_f32_16x16x32_bf16 v[124:127], v[134:137], v[176:179], v[124:127]
	v_mfma_f32_16x16x32_bf16 v[120:123], v[142:145], v[176:179], v[120:123]
	v_mfma_f32_16x16x32_bf16 v[108:111], v[134:137], v[184:187], v[108:111]
	v_mfma_f32_16x16x32_bf16 v[104:107], v[142:145], v[184:187], v[104:107]
	v_mfma_f32_16x16x32_bf16 v[92:95], v[134:137], v[192:195], v[92:95]
	v_mfma_f32_16x16x32_bf16 v[88:91], v[142:145], v[192:195], v[88:91]
	v_mfma_f32_16x16x32_bf16 v[76:79], v[134:137], v[204:207], v[76:79]
	v_mfma_f32_16x16x32_bf16 v[72:75], v[142:145], v[204:207], v[72:75]
	v_mfma_f32_16x16x32_bf16 v[116:119], v[156:159], v[172:175], v[116:119]
	v_mfma_f32_16x16x32_bf16 v[112:115], v[164:167], v[172:175], v[112:115]
	v_mfma_f32_16x16x32_bf16 v[100:103], v[156:159], v[180:183], v[100:103]
	v_mfma_f32_16x16x32_bf16 v[96:99], v[164:167], v[180:183], v[96:99]
	v_mfma_f32_16x16x32_bf16 v[84:87], v[156:159], v[188:191], v[84:87]
	v_mfma_f32_16x16x32_bf16 v[80:83], v[164:167], v[188:191], v[80:83]
	v_mfma_f32_16x16x32_bf16 v[68:71], v[156:159], v[196:199], v[68:71]
	v_mfma_f32_16x16x32_bf16 v[64:67], v[164:167], v[196:199], v[64:67]
	v_mfma_f32_16x16x32_bf16 v[116:119], v[160:163], v[176:179], v[116:119]
	v_mfma_f32_16x16x32_bf16 v[112:115], v[168:171], v[176:179], v[112:115]
	v_mfma_f32_16x16x32_bf16 v[100:103], v[160:163], v[184:187], v[100:103]
	v_mfma_f32_16x16x32_bf16 v[96:99], v[168:171], v[184:187], v[96:99]
	v_mfma_f32_16x16x32_bf16 v[84:87], v[160:163], v[192:195], v[84:87]
	v_mfma_f32_16x16x32_bf16 v[80:83], v[168:171], v[192:195], v[80:83]
	v_mfma_f32_16x16x32_bf16 v[68:71], v[160:163], v[204:207], v[68:71]
	v_mfma_f32_16x16x32_bf16 v[64:67], v[168:171], v[204:207], v[64:67]
	s_barrier
	s_add_i32 s8, s8, s14
	v_lshl_add_u64 v[208:209], s[46:47], 0, v[128:129]
	s_mov_b32 m0, s8
	ds_read_b128 v[172:175], v203 offset:16384
	ds_read_b128 v[176:179], v203 offset:17408
	ds_read_b128 v[180:183], v203 offset:18432
	ds_read_b128 v[184:187], v203 offset:19456
	ds_read_b128 v[188:191], v203 offset:20480
	ds_read_b128 v[192:195], v203 offset:21504
	ds_read_b128 v[196:199], v203 offset:22528
	ds_read_b128 v[204:207], v203 offset:23552
	global_load_lds_dwordx4 v[208:209], off
	s_add_i32 m0, s8, 0x2000
	s_add_u32 s96, s46, 0xb0000
	v_lshl_add_u64 v[210:211], s[46:47], 0, v[146:147]
	s_addc_u32 s97, s47, 0
	s_add_i32 s8, s85, s14
	global_load_lds_dwordx4 v[210:211], off
	v_lshl_add_u64 v[214:215], s[96:97], 0, v[128:129]
	s_mov_b32 m0, s8
	v_lshl_add_u64 v[222:223], s[64:65], 0, v[148:149]
	global_load_lds_dwordx4 v[214:215], off
	v_lshl_add_u64 v[214:215], s[96:97], 0, v[146:147]
	s_add_i32 m0, s8, 0x2000
	s_nop 0
	global_load_lds_dwordx4 v[214:215], off
	v_lshl_add_u64 v[214:215], s[64:65], 0, v[150:151]
	s_mov_b32 m0, s15
	s_nop 0
	global_load_lds_dwordx4 v[214:215], off
	s_mov_b32 m0, s18
	s_nop 0
	global_load_lds_dwordx4 v[222:223], off
	s_nop 0
	s_waitcnt vmcnt(8)
	s_waitcnt lgkmcnt(0)
	s_barrier
; #define PG8_STAGE(bufoff, gbase, voff) do { _Pragma("unroll") for (int _i = 0; _i < 2; ++_i) \
;         __builtin_amdgcn_global_load_lds((const unsigned*)((const char*)(gbase) + (voff)[_i]), (PG8_LAS unsigned*)(lds + (bufoff) + ldsw + _i * 8192), 16, 0, 0); } while (0)
; #define PG8_LDA(dst, b, h) do { _Pragma("unroll") for (int m = 0; m < 4; ++m) _Pragma("unroll") for (int k = 0; k < 2; ++k) dst[m][k] = *(const PG8_LAS bf16x8*)(lds + PG8_SA(b, h) + aoff + m * 2048 + k * 1024); } while (0)
; #define PG8_LDB(dst, b, h) do { _Pragma("unroll") for (int n = 0; n < 2; ++n) _Pragma("unroll") for (int k = 0; k < 2; ++k) dst[n][k] = *(const PG8_LAS bf16x8*)(lds + PG8_SB(b, h) + boff + n * 2048 + k * 1024); } while (0)
; #define PG8_MMA(ai, bj, At, Bt) do { __builtin_amdgcn_s_setprio(1); _Pragma("unroll") for (int m = 0; m < 4; ++m) _Pragma("unroll") for (int n = 0; n < 2; ++n) _Pragma("unroll") for (int k = 0; k < 2; ++k) \
;         acc[ai][bj][m][n] = __builtin_amdgcn_mfma_f32_16x16x32_bf16(Bt[n][k], At[m][k], acc[ai][bj][m][n], 0, 0, 0); __builtin_amdgcn_s_setprio(0); } while (0)
; #define PG8_WAIT_V(n) asm volatile("s_waitcnt vmcnt(" #n ")" ::: "memory")
; #define PG8_WAIT_L(n) asm volatile("s_waitcnt lgkmcnt(" #n ")" ::: "memory")
; #define PG8_BAR __builtin_amdgcn_s_barrier()
; #define PG8_SCHED __builtin_amdgcn_sched_barrier(0)
; template <class Epi, class Sched, bool ALIGN_EPI = false, bool SP2 = false>
; __device__ __forceinline__ void gemm_phase(PG8_LAS unsigned char* lds, const Gemm g, const Sched& S, const Epi& E) {
;     ...
;             PG8_WAIT_V(8); PG8_WAIT_L(0); PG8_BAR; PG8_MMA(1, 0, At, B0); PG8_MMA(1, 1, At, B1); PG8_BAR; PG8_SCHED;
;             PG8_LDB(B0, 1, 0); PG8_LDB(B1, 1, 1); PG8_SCHED; PG8_LDA(At, 1, 0); PG8_STAGE(PG8_SA(0, 1), a2 + hstep, voffA);
;             PG8_WAIT_V(8); PG8_WAIT_L(0); PG8_BAR; PG8_MMA(0, 0, At, B0); PG8_MMA(0, 1, At, B1); PG8_BAR; PG8_SCHED;
	s_waitcnt lgkmcnt(0)
	v_mfma_f32_16x16x32_bf16 v[60:63], v[130:133], v[172:175], v[60:63]
	v_mfma_f32_16x16x32_bf16 v[56:59], v[138:141], v[172:175], v[56:59]
	v_mfma_f32_16x16x32_bf16 v[44:47], v[130:133], v[180:183], v[44:47]
	v_mfma_f32_16x16x32_bf16 v[40:43], v[138:141], v[180:183], v[40:43]
	v_mfma_f32_16x16x32_bf16 v[28:31], v[130:133], v[188:191], v[28:31]
	v_mfma_f32_16x16x32_bf16 v[24:27], v[138:141], v[188:191], v[24:27]
	v_mfma_f32_16x16x32_bf16 v[12:15], v[130:133], v[196:199], v[12:15]
	v_mfma_f32_16x16x32_bf16 v[8:11], v[138:141], v[196:199], v[8:11]
	v_mfma_f32_16x16x32_bf16 v[60:63], v[134:137], v[176:179], v[60:63]
	v_mfma_f32_16x16x32_bf16 v[56:59], v[142:145], v[176:179], v[56:59]
	v_mfma_f32_16x16x32_bf16 v[44:47], v[134:137], v[184:187], v[44:47]
	v_mfma_f32_16x16x32_bf16 v[40:43], v[142:145], v[184:187], v[40:43]
	v_mfma_f32_16x16x32_bf16 v[28:31], v[134:137], v[192:195], v[28:31]
	v_mfma_f32_16x16x32_bf16 v[24:27], v[142:145], v[192:195], v[24:27]
	v_mfma_f32_16x16x32_bf16 v[12:15], v[134:137], v[204:207], v[12:15]
	v_mfma_f32_16x16x32_bf16 v[8:11], v[142:145], v[204:207], v[8:11]
	v_mfma_f32_16x16x32_bf16 v[52:55], v[156:159], v[172:175], v[52:55]
	v_mfma_f32_16x16x32_bf16 v[48:51], v[164:167], v[172:175], v[48:51]
	v_mfma_f32_16x16x32_bf16 v[36:39], v[156:159], v[180:183], v[36:39]
	v_mfma_f32_16x16x32_bf16 v[32:35], v[164:167], v[180:183], v[32:35]
	v_mfma_f32_16x16x32_bf16 v[20:23], v[156:159], v[188:191], v[20:23]
	v_mfma_f32_16x16x32_bf16 v[16:19], v[164:167], v[188:191], v[16:19]
	v_mfma_f32_16x16x32_bf16 v[4:7], v[156:159], v[196:199], v[4:7]
	v_mfma_f32_16x16x32_bf16 v[0:3], v[164:167], v[196:199], v[0:3]
	v_mfma_f32_16x16x32_bf16 v[52:55], v[160:163], v[176:179], v[52:55]
	v_mfma_f32_16x16x32_bf16 v[48:51], v[168:171], v[176:179], v[48:51]
	v_mfma_f32_16x16x32_bf16 v[36:39], v[160:163], v[184:187], v[36:39]
	v_mfma_f32_16x16x32_bf16 v[32:35], v[168:171], v[184:187], v[32:35]
	v_mfma_f32_16x16x32_bf16 v[20:23], v[160:163], v[192:195], v[20:23]
	v_mfma_f32_16x16x32_bf16 v[16:19], v[168:171], v[192:195], v[16:19]
	v_mfma_f32_16x16x32_bf16 v[4:7], v[160:163], v[204:207], v[4:7]
	v_mfma_f32_16x16x32_bf16 v[0:3], v[168:171], v[204:207], v[0:3]
	s_barrier
	s_add_i32 s8, 0, 0x18000
	s_add_i32 s85, 0, 0x1c000
	v_add_u32_e32 v142, s8, v201
	v_add_u32_e32 v168, s85, v201
	ds_read_b128 v[130:133], v142
	ds_read_b128 v[134:137], v142 offset:1024
	ds_read_b128 v[138:141], v142 offset:2048
	ds_read_b128 v[142:145], v142 offset:3072
	ds_read_b128 v[156:159], v168
	ds_read_b128 v[160:163], v168 offset:1024
	ds_read_b128 v[164:167], v168 offset:2048
	ds_read_b128 v[168:171], v168 offset:3072
	s_add_u32 s64, s64, 0xb0000
	s_addc_u32 s65, s65, 0
	s_mov_b32 m0, s19
	v_lshl_add_u64 v[228:229], s[64:65], 0, v[150:151]
	ds_read_b128 v[172:175], v203 offset:32768
	ds_read_b128 v[176:179], v203 offset:33792
	ds_read_b128 v[180:183], v203 offset:34816
	ds_read_b128 v[184:187], v203 offset:35840
	ds_read_b128 v[188:191], v203 offset:36864
	ds_read_b128 v[192:195], v203 offset:37888
	ds_read_b128 v[196:199], v203 offset:38912
	ds_read_b128 v[204:207], v203 offset:39936
	global_load_lds_dwordx4 v[228:229], off
	v_lshl_add_u64 v[228:229], s[64:65], 0, v[148:149]
	s_mov_b32 m0, s20
	s_nop 0
	global_load_lds_dwordx4 v[228:229], off
	s_nop 0
	s_waitcnt vmcnt(8)
	s_waitcnt lgkmcnt(0)
	s_barrier
	s_waitcnt lgkmcnt(0)
	v_mfma_f32_16x16x32_bf16 v[124:127], v[130:133], v[172:175], v[124:127]
	v_mfma_f32_16x16x32_bf16 v[120:123], v[138:141], v[172:175], v[120:123]
	v_mfma_f32_16x16x32_bf16 v[108:111], v[130:133], v[180:183], v[108:111]
	v_mfma_f32_16x16x32_bf16 v[104:107], v[138:141], v[180:183], v[104:107]
	v_mfma_f32_16x16x32_bf16 v[92:95], v[130:133], v[188:191], v[92:95]
	v_mfma_f32_16x16x32_bf16 v[88:91], v[138:141], v[188:191], v[88:91]
	v_mfma_f32_16x16x32_bf16 v[76:79], v[130:133], v[196:199], v[76:79]
	v_mfma_f32_16x16x32_bf16 v[72:75], v[138:141], v[196:199], v[72:75]
	v_mfma_f32_16x16x32_bf16 v[124:127], v[134:137], v[176:179], v[124:127]
	v_mfma_f32_16x16x32_bf16 v[120:123], v[142:145], v[176:179], v[120:123]
	v_mfma_f32_16x16x32_bf16 v[108:111], v[134:137], v[184:187], v[108:111]
	v_mfma_f32_16x16x32_bf16 v[104:107], v[142:145], v[184:187], v[104:107]
	v_mfma_f32_16x16x32_bf16 v[92:95], v[134:137], v[192:195], v[92:95]
	v_mfma_f32_16x16x32_bf16 v[88:91], v[142:145], v[192:195], v[88:91]
	v_mfma_f32_16x16x32_bf16 v[76:79], v[134:137], v[204:207], v[76:79]
	v_mfma_f32_16x16x32_bf16 v[72:75], v[142:145], v[204:207], v[72:75]
	v_mfma_f32_16x16x32_bf16 v[116:119], v[156:159], v[172:175], v[116:119]
	v_mfma_f32_16x16x32_bf16 v[112:115], v[164:167], v[172:175], v[112:115]
	v_mfma_f32_16x16x32_bf16 v[100:103], v[156:159], v[180:183], v[100:103]
	v_mfma_f32_16x16x32_bf16 v[96:99], v[164:167], v[180:183], v[96:99]
	v_mfma_f32_16x16x32_bf16 v[84:87], v[156:159], v[188:191], v[84:87]
	v_mfma_f32_16x16x32_bf16 v[80:83], v[164:167], v[188:191], v[80:83]
	v_mfma_f32_16x16x32_bf16 v[68:71], v[156:159], v[196:199], v[68:71]
	v_mfma_f32_16x16x32_bf16 v[64:67], v[164:167], v[196:199], v[64:67]
	v_mfma_f32_16x16x32_bf16 v[116:119], v[160:163], v[176:179], v[116:119]
	v_mfma_f32_16x16x32_bf16 v[112:115], v[168:171], v[176:179], v[112:115]
	v_mfma_f32_16x16x32_bf16 v[100:103], v[160:163], v[184:187], v[100:103]
	v_mfma_f32_16x16x32_bf16 v[96:99], v[168:171], v[184:187], v[96:99]
	v_mfma_f32_16x16x32_bf16 v[84:87], v[160:163], v[192:195], v[84:87]
	v_mfma_f32_16x16x32_bf16 v[80:83], v[168:171], v[192:195], v[80:83]
	v_mfma_f32_16x16x32_bf16 v[68:71], v[160:163], v[204:207], v[68:71]
	v_mfma_f32_16x16x32_bf16 v[64:67], v[168:171], v[204:207], v[64:67]
	s_barrier
; #define PG8_STAGE(bufoff, gbase, voff) do { _Pragma("unroll") for (int _i = 0; _i < 2; ++_i) \
;         __builtin_amdgcn_global_load_lds((const unsigned*)((const char*)(gbase) + (voff)[_i]), (PG8_LAS unsigned*)(lds + (bufoff) + ldsw + _i * 8192), 16, 0, 0); } while (0)
; #define PG8_LDA(dst, b, h) do { _Pragma("unroll") for (int m = 0; m < 4; ++m) _Pragma("unroll") for (int k = 0; k < 2; ++k) dst[m][k] = *(const PG8_LAS bf16x8*)(lds + PG8_SA(b, h) + aoff + m * 2048 + k * 1024); } while (0)
; #define PG8_MMA(ai, bj, At, Bt) do { __builtin_amdgcn_s_setprio(1); _Pragma("unroll") for (int m = 0; m < 4; ++m) _Pragma("unroll") for (int n = 0; n < 2; ++n) _Pragma("unroll") for (int k = 0; k < 2; ++k) \
;         acc[ai][bj][m][n] = __builtin_amdgcn_mfma_f32_16x16x32_bf16(Bt[n][k], At[m][k], acc[ai][bj][m][n], 0, 0, 0); __builtin_amdgcn_s_setprio(0); } while (0)
; #define PG8_WAIT_V(n) asm volatile("s_waitcnt vmcnt(" #n ")" ::: "memory")
; #define PG8_WAIT_L(n) asm volatile("s_waitcnt lgkmcnt(" #n ")" ::: "memory")
; #define PG8_BAR __builtin_amdgcn_s_barrier()
; #define PG8_SCHED __builtin_amdgcn_sched_barrier(0)
; template <class Epi, class Sched, bool ALIGN_EPI = false, bool SP2 = false>
; __device__ __forceinline__ void gemm_phase(PG8_LAS unsigned char* lds, const Gemm g, const Sched& S, const Epi& E) {
;     ...
;             PG8_LDA(At, 1, 1); PG8_STAGE(PG8_SB(1, 0), b3, voffB); PG8_STAGE(PG8_SB(1, 1), b3 + hstep, voffB); PG8_STAGE(PG8_SA(1, 0), a3, voffA);
;             PG8_WAIT_V(8); PG8_WAIT_L(0); PG8_BAR; PG8_MMA(1, 0, At, B0); PG8_MMA(1, 1, At, B1); PG8_BAR; PG8_SCHED;
	s_add_i32 s8, s8, s14
	v_lshl_add_u64 v[208:209], v[208:209], 0, s[90:91]
	s_mov_b32 m0, s8
	ds_read_b128 v[172:175], v203 offset:49152
	ds_read_b128 v[176:179], v203 offset:50176
	ds_read_b128 v[180:183], v203 offset:51200
	ds_read_b128 v[184:187], v203 offset:52224
	ds_read_b128 v[188:191], v203 offset:53248
	ds_read_b128 v[192:195], v203 offset:54272
	ds_read_b128 v[196:199], v203 offset:55296
	ds_read_b128 v[204:207], v203 offset:56320
	global_load_lds_dwordx4 v[208:209], off
	s_add_i32 m0, s8, 0x2000
	s_add_u32 s46, s46, 0xb0080
	v_lshl_add_u64 v[208:209], v[210:211], 0, s[90:91]
	s_addc_u32 s47, s47, 0
	s_add_i32 s8, s85, s14
	global_load_lds_dwordx4 v[208:209], off
	v_lshl_add_u64 v[208:209], s[46:47], 0, v[128:129]
	s_mov_b32 m0, s8
	s_nop 0
	global_load_lds_dwordx4 v[208:209], off
	v_lshl_add_u64 v[208:209], s[46:47], 0, v[146:147]
	s_add_i32 m0, s8, 0x2000
	s_nop 0
	global_load_lds_dwordx4 v[208:209], off
	v_lshl_add_u64 v[208:209], v[214:215], 0, s[90:91]
	s_mov_b32 m0, s29
	s_nop 0
	global_load_lds_dwordx4 v[208:209], off
	v_lshl_add_u64 v[208:209], v[222:223], 0, s[90:91]
	s_mov_b32 m0, s30
	s_nop 0
	global_load_lds_dwordx4 v[208:209], off
	s_waitcnt vmcnt(8)
	s_waitcnt lgkmcnt(0)
	s_barrier
	s_waitcnt lgkmcnt(0)
	v_mfma_f32_16x16x32_bf16 v[60:63], v[130:133], v[172:175], v[60:63]
	v_mfma_f32_16x16x32_bf16 v[56:59], v[138:141], v[172:175], v[56:59]
	v_mfma_f32_16x16x32_bf16 v[44:47], v[130:133], v[180:183], v[44:47]
	v_mfma_f32_16x16x32_bf16 v[40:43], v[138:141], v[180:183], v[40:43]
	v_mfma_f32_16x16x32_bf16 v[28:31], v[130:133], v[188:191], v[28:31]
	v_mfma_f32_16x16x32_bf16 v[24:27], v[138:141], v[188:191], v[24:27]
	v_mfma_f32_16x16x32_bf16 v[12:15], v[130:133], v[196:199], v[12:15]
	v_mfma_f32_16x16x32_bf16 v[8:11], v[138:141], v[196:199], v[8:11]
	v_mfma_f32_16x16x32_bf16 v[60:63], v[134:137], v[176:179], v[60:63]
	v_mfma_f32_16x16x32_bf16 v[56:59], v[142:145], v[176:179], v[56:59]
	v_mfma_f32_16x16x32_bf16 v[44:47], v[134:137], v[184:187], v[44:47]
	v_mfma_f32_16x16x32_bf16 v[40:43], v[142:145], v[184:187], v[40:43]
	v_mfma_f32_16x16x32_bf16 v[28:31], v[134:137], v[192:195], v[28:31]
	v_mfma_f32_16x16x32_bf16 v[24:27], v[142:145], v[192:195], v[24:27]
	v_mfma_f32_16x16x32_bf16 v[12:15], v[134:137], v[204:207], v[12:15]
	v_mfma_f32_16x16x32_bf16 v[8:11], v[142:145], v[204:207], v[8:11]
	v_mfma_f32_16x16x32_bf16 v[52:55], v[156:159], v[172:175], v[52:55]
	v_mfma_f32_16x16x32_bf16 v[48:51], v[164:167], v[172:175], v[48:51]
	v_mfma_f32_16x16x32_bf16 v[36:39], v[156:159], v[180:183], v[36:39]
	v_mfma_f32_16x16x32_bf16 v[32:35], v[164:167], v[180:183], v[32:35]
	v_mfma_f32_16x16x32_bf16 v[20:23], v[156:159], v[188:191], v[20:23]
	v_mfma_f32_16x16x32_bf16 v[16:19], v[164:167], v[188:191], v[16:19]
	v_mfma_f32_16x16x32_bf16 v[4:7], v[156:159], v[196:199], v[4:7]
	v_mfma_f32_16x16x32_bf16 v[0:3], v[164:167], v[196:199], v[0:3]
	v_mfma_f32_16x16x32_bf16 v[52:55], v[160:163], v[176:179], v[52:55]
	v_mfma_f32_16x16x32_bf16 v[48:51], v[168:171], v[176:179], v[48:51]
	v_mfma_f32_16x16x32_bf16 v[36:39], v[160:163], v[184:187], v[36:39]
	v_mfma_f32_16x16x32_bf16 v[32:35], v[168:171], v[184:187], v[32:35]
	v_mfma_f32_16x16x32_bf16 v[20:23], v[160:163], v[192:195], v[20:23]
	v_mfma_f32_16x16x32_bf16 v[16:19], v[168:171], v[192:195], v[16:19]
	v_mfma_f32_16x16x32_bf16 v[4:7], v[160:163], v[204:207], v[4:7]
	v_mfma_f32_16x16x32_bf16 v[0:3], v[168:171], v[204:207], v[0:3]
	s_barrier
	s_add_i32 s84, s84, 2
	s_add_u32 s36, s36, 0x100
	s_addc_u32 s37, s37, 0
	s_cmp_gt_u32 s84, 41
	s_mov_b64 s[96:97], s[42:43]
	s_cbranch_scc0 .LBB0_995
	s_setprio 0
	s_and_b64 vcc, exec, s[62:63]
	s_cbranch_vccz .LBB0_998
	s_barrier
